# attention: V stored to LDS without the key bit-swap so packed P feeds the PV MFMA directly (8 v_permlane32_swap per tile removed)
# baseline (speedup 1.0000x reference)
; __device__ __forceinline__ float bflo(unsigned w) { return __uint_as_float(w << 16); }
; __device__ __forceinline__ float bfhi(unsigned w) { return __uint_as_float(w & 0xffff0000u); }
; __device__ __forceinline__ int v_st(int k, int c) { const int kk = (k & ~0xC) | ((k & 4) << 1) | ((k & 8) >> 1); return ((kk >> 3) * 4 + (c >> 5)) * 512 + ((kk & 7) * 32 + (c & 31)) * 2; }
; __device__ __forceinline__ int v_rd_base(int lane) { return ((lane & 3) << 3) | (((lane >> 2) & 3) << 6) | (((lane >> 4) & 1) << 5) | (((lane >> 5) & 1) << 8); }
; #define SLOAD(i, k0) do { sr_[i].vs0 = LD8(&Vh[(long)((k0) + sr) * LDK + sc]); sr_[i].vs1 = LD8(&Vh[(long)((k0) + 32 + sr) * LDK + sc]); \
;     sr_[i].ks0 = LD8(&Kh[(long)((k0) + sr) * LDK + sc]); sr_[i].ks1 = LD8(&Kh[(long)((k0) + 32 + sr) * LDK + sc]); } while (0)
; __device__ __forceinline__ void attn_body(const bf16_t* __restrict__ Qb, const bf16_t* __restrict__ Kh, const bf16_t* __restrict__ Vh, const bf16_t* __restrict__ Zb, ...
;     ...
;     float l_reg = 0; f32x16 o[4] = {}; bf16x8 qr[8];
;     const bf16_t* Qw = Qb + (long)(wid * QBLK + r32) * LDQ + hi * 8;
; #pragma unroll
;     for (int d0 = 0; d0 < 8; ++d0) qr[d0] = *reinterpret_cast<const bf16x8*>(Qw + d0 * 16);
;     const int sr = tid >> 4, sc = (tid & 15) * 8, vst0 = v_st(sr, sc), vst1 = v_st(32 + sr, sc);
;     const int vb0 = (int)(uintptr_t)V_lds + v_rd_base(lane);
;     struct { bf16x8 vs0, vs1, ks0, ks1; } sr_[2];
;     ...
;     SLOAD(0, 0); SLOAD(1, KVBLK);
;     {
;         float ss = 0.f; int hi_ = hi; const float* qg_ = qg;
;         asm volatile("" : "+v"(hi_)); asm volatile("" : "+s"(qg_));
; #pragma unroll
;         for (int d0 = 0; d0 < 8; ++d0) { const u32x4 w = *reinterpret_cast<const u32x4*>(&qr[d0]);
;             ss += bflo(w.x) * bflo(w.x) + bfhi(w.x) * bfhi(w.x) + bflo(w.y) * bflo(w.y) + bfhi(w.y) * bfhi(w.y) + bflo(w.z) * bflo(w.z) + bfhi(w.z) * bfhi(w.z) + bflo(w.w) * bflo(w.w) + bfhi(w.w) * bfhi(w.w); }
;         ss += __shfl_xor(ss, 32);
;         const float rinv = rsqrtf(ss * (1.f / 128.f) + 1e-6f) * (SCALE * 1.4426950408889634f);
;         const int tpos = tq0 + wid * QBLK + r32; const float* rope_ = rope; asm volatile("" : "+s"(rope_));
.LBB0_485:
	s_lshl_b32 s23, s7, 8
	s_and_b32 s20, s8, 1
	s_add_i32 s8, s23, s22
	s_mul_i32 s16, s8, 0x1800
	s_mul_hi_u32 s7, s8, 0x1800
	s_add_u32 s16, s78, s16
	s_addc_u32 s17, s79, s7
	s_lshl_b32 s7, s20, 9
	s_lshl_b32 s6, s6, 7
	s_add_i32 s6, s6, s7
	s_mov_b32 s7, s9
	s_lshl_b64 s[18:19], s[6:7], 1
	s_add_u32 s16, s16, s18
	v_mov_b32_e32 v200, v176
	s_addc_u32 s17, s17, s19
	v_mov_b64_e32 v[0:1], s[16:17]
	v_ashrrev_i32_e32 v2, 1, v200
	v_bfe_u32 v199, v200, 5, 1
	v_bfi_b32 v3, s25, v2, v200
	v_mad_i64_i32 v[0:1], s[6:7], v3, s30, v[0:1]
	v_lshlrev_b32_e32 v184, 4, v199
	v_lshl_add_u64 v[0:1], v[0:1], 0, v[184:185]
	global_load_dwordx4 v[74:77], v[0:1], off offset:160
	global_load_dwordx4 v[78:81], v[0:1], off offset:128
	global_load_dwordx4 v[40:43], v[0:1], off
	global_load_dwordx4 v[32:35], v[0:1], off offset:32
	global_load_dwordx4 v[44:47], v[0:1], off offset:64
	global_load_dwordx4 v[36:39], v[0:1], off offset:96
	global_load_dwordx4 v[56:59], v[0:1], off offset:192
	global_load_dwordx4 v[94:97], v[0:1], off offset:224
	v_ashrrev_i32_e32 v186, 4, v200
	v_and_b32_e32 v202, 0xffffffe0, v2
	v_and_b32_e32 v1, 0xfffff0, v186
	v_lshlrev_b32_e32 v2, 1, v186
	v_lshlrev_b32_e32 v0, 3, v200
	v_and_or_b32 v1, v2, 8, v1
	v_lshrrev_b32_e32 v61, 1, v1
	v_bfe_u32 v62, v0, 5, 2
	v_or_b32_e32 v61, v61, v62
	v_lshrrev_b32_e32 v60, 1, v186
	v_lshlrev_b32_e32 v92, 9, v61
	v_and_b32_e32 v61, 3, v186
	v_add_u32_e32 v189, 32, v186
	v_and_or_b32 v60, v60, 4, v61
	v_lshlrev_b32_e32 v93, 6, v60
	v_and_b32_e32 v60, 0xfffff0, v189
	v_lshlrev_b32_e32 v61, 1, v189
	v_and_or_b32 v60, v61, 8, v60
	s_mul_i32 s7, s22, 0x1800
	v_lshrrev_b32_e32 v60, 1, v60
	s_mul_hi_u32 s6, s22, 0x1800
	s_add_u32 s7, s78, s7
	v_or_b32_e32 v60, v60, v62
	s_addc_u32 s6, s79, s6
	s_lshl_b32 s41, s20, 8
	v_lshlrev_b32_e32 v107, 9, v60
	s_add_u32 s20, s7, s41
	v_add_u32_e32 v16, 64, v186
	s_addc_u32 s21, s6, 0
	v_and_b32_e32 v198, 0x78, v0
	v_mad_i64_i32 v[16:17], s[6:7], v16, s31, 0
	v_or_b32_e32 v16, v16, v198
	v_lshl_add_u64 v[20:21], v[16:17], 1, s[20:21]
	v_add_u32_e32 v16, 0x60, v186
	v_mad_i64_i32 v[0:1], s[6:7], v186, s31, 0
	v_mad_i64_i32 v[2:3], s[6:7], v189, s31, 0
	v_mad_i64_i32 v[16:17], s[6:7], v16, s31, 0
	v_or_b32_e32 v0, v0, v198
	v_or_b32_e32 v2, v2, v198
	v_or_b32_e32 v16, v16, v198
	v_lshl_add_u64 v[0:1], v[0:1], 1, s[20:21]
	v_lshl_add_u64 v[2:3], v[2:3], 1, s[20:21]
	v_lshl_add_u64 v[24:25], v[16:17], 1, s[20:21]
	v_mov_b32_e32 v106, v199
	v_readlane_b32 s44, v254, 27
	v_cmp_lt_i32_e32 vcc, v179, v195
	v_and_b32_e32 v201, 31, v200
	global_load_dwordx4 v[8:11], v[0:1], off offset:2560
	global_load_dwordx4 v[4:7], v[0:1], off offset:2048
	global_load_dwordx4 v[12:15], v[2:3], off offset:2560
	s_nop 0
	global_load_dwordx4 v[0:3], v[2:3], off offset:2048
	s_nop 0
	global_load_dwordx4 v[16:19], v[20:21], off offset:2560
	s_nop 0
	global_load_dwordx4 v[20:23], v[20:21], off offset:2048
	s_nop 0
	global_load_dwordx4 v[28:31], v[24:25], off offset:2560
	s_nop 0
	global_load_dwordx4 v[24:27], v[24:25], off offset:2048
	v_readlane_b32 s58, v254, 41
	v_readlane_b32 s59, v254, 42
	v_lshlrev_b32_e32 v48, 3, v106
	s_mov_b64 s[42:43], s[58:59]
	v_ashrrev_i32_e32 v49, 31, v48
	s_mov_b64 s[6:7], s[10:11]
	v_lshl_add_u64 v[68:69], v[48:49], 2, s[42:43]
	flat_load_dwordx4 v[98:101], v[68:69] offset:128
	flat_load_dwordx4 v[102:105], v[68:69] offset:144
	flat_load_dwordx4 v[52:55], v[68:69]
	flat_load_dwordx4 v[48:51], v[68:69] offset:16
	v_lshlrev_b32_e32 v165, 4, v106
	v_lshlrev_b32_e32 v188, 1, v198
	v_readlane_b32 s45, v254, 28
	v_readlane_b32 s46, v254, 29
	v_readlane_b32 s47, v254, 30
	v_readlane_b32 s48, v254, 31
	v_readlane_b32 s49, v254, 32
	v_readlane_b32 s50, v254, 33
	v_readlane_b32 s51, v254, 34
	v_readlane_b32 s52, v254, 35
	s_waitcnt vmcnt(0)
	v_lshlrev_b32_e32 v125, 16, v43
	v_and_b32_e32 v129, 0xffff0000, v43
	v_lshlrev_b32_e32 v131, 16, v42
	v_and_b32_e32 v63, 0xffff0000, v74
	v_and_b32_e32 v62, 0xffff0000, v78
	v_lshlrev_b32_e32 v61, 16, v74
	v_lshlrev_b32_e32 v60, 16, v78
	v_pk_mul_f32 v[64:65], v[62:63], v[62:63]
	v_and_b32_e32 v85, 0xffff0000, v94
	v_pk_fma_f32 v[66:67], v[60:61], v[60:61], v[64:65]
	v_lshlrev_b32_e32 v65, 16, v75
	v_lshlrev_b32_e32 v64, 16, v79
	v_pk_fma_f32 v[70:71], v[64:65], v[64:65], v[66:67]
	v_and_b32_e32 v67, 0xffff0000, v75
	v_and_b32_e32 v66, 0xffff0000, v79
	v_pk_fma_f32 v[72:73], v[66:67], v[66:67], v[70:71]
	v_lshlrev_b32_e32 v71, 16, v76
	v_lshlrev_b32_e32 v70, 16, v80
	v_pk_fma_f32 v[74:75], v[70:71], v[70:71], v[72:73]
	v_and_b32_e32 v73, 0xffff0000, v76
	v_and_b32_e32 v72, 0xffff0000, v80
	v_pk_fma_f32 v[78:79], v[72:73], v[72:73], v[74:75]
	v_lshlrev_b32_e32 v75, 16, v77
	v_lshlrev_b32_e32 v74, 16, v81
	v_pk_fma_f32 v[78:79], v[74:75], v[74:75], v[78:79]
	v_and_b32_e32 v77, 0xffff0000, v77
	v_and_b32_e32 v76, 0xffff0000, v81
	v_and_b32_e32 v84, 0xffff0000, v56
	v_pk_fma_f32 v[122:123], v[76:77], v[76:77], v[78:79]
	v_lshlrev_b32_e32 v83, 16, v94
	v_lshlrev_b32_e32 v82, 16, v56
	v_pk_mul_f32 v[78:79], v[84:85], v[84:85]
	v_lshlrev_b32_e32 v87, 16, v95
	v_pk_fma_f32 v[78:79], v[82:83], v[82:83], v[78:79]
	v_lshlrev_b32_e32 v86, 16, v57
	v_lshlrev_b32_e32 v90, 16, v58
	v_and_b32_e32 v80, 0xffff0000, v58
	v_cndmask_b32_e32 v58, v177, v179, vcc
	v_pk_fma_f32 v[78:79], v[86:87], v[86:87], v[78:79]
	v_and_b32_e32 v89, 0xffff0000, v95
	v_and_b32_e32 v88, 0xffff0000, v57
	v_lshlrev_b32_e32 v135, 2, v58
	v_or_b32_e32 v58, s23, v201
	v_pk_fma_f32 v[56:57], v[88:89], v[88:89], v[78:79]
	v_lshlrev_b32_e32 v91, 16, v96
	v_add_u32_e32 v164, v58, v202
	v_pk_fma_f32 v[56:57], v[90:91], v[90:91], v[56:57]
	v_and_b32_e32 v81, 0xffff0000, v96
; __device__ __forceinline__ float bflo(unsigned w) { return __uint_as_float(w << 16); }
; __device__ __forceinline__ float bfhi(unsigned w) { return __uint_as_float(w & 0xffff0000u); }
; __device__ __forceinline__ void attn_body(const bf16_t* __restrict__ Qb, const bf16_t* __restrict__ Kh, const bf16_t* __restrict__ Vh, const bf16_t* __restrict__ Zb, ...
;     ...
;         float ss = 0.f; int hi_ = hi; const float* qg_ = qg;
;         asm volatile("" : "+v"(hi_)); asm volatile("" : "+s"(qg_));
; #pragma unroll
;         for (int d0 = 0; d0 < 8; ++d0) { const u32x4 w = *reinterpret_cast<const u32x4*>(&qr[d0]);
;             ss += bflo(w.x) * bflo(w.x) + bfhi(w.x) * bfhi(w.x) + bflo(w.y) * bflo(w.y) + bfhi(w.y) * bfhi(w.y) + bflo(w.z) * bflo(w.z) + bfhi(w.z) * bfhi(w.z) + bflo(w.w) * bflo(w.w) + bfhi(w.w) * bfhi(w.w); }
;         ss += __shfl_xor(ss, 32);
;         const float rinv = rsqrtf(ss * (1.f / 128.f) + 1e-6f) * (SCALE * 1.4426950408889634f);
;         const int tpos = tq0 + wid * QBLK + r32; const float* rope_ = rope; asm volatile("" : "+s"(rope_));
; #pragma unroll
;         for (int ax = 0; ax < 2; ++ax)
; #pragma unroll
;             for (int dd = 0; dd < 2; ++dd) { const int da = ax * 4 + dd, db = da + 2;
;                 const u32x4 wa = *reinterpret_cast<const u32x4*>(&qr[da]), wb = *reinterpret_cast<const u32x4*>(&qr[db]);
;                 float xa[8] = {bflo(wa.x), bfhi(wa.x), bflo(wa.y), bfhi(wa.y), bflo(wa.z), bfhi(wa.z), bflo(wa.w), bfhi(wa.w)};
;                 float xb[8] = {bflo(wb.x), bfhi(wb.x), bflo(wb.y), bfhi(wb.y), bflo(wb.z), bfhi(wb.z), bflo(wb.w), bfhi(wb.w)};
;                 const float* ga = qg_ + da * 16 + hi_ * 8; const float* gb = qg_ + db * 16 + hi_ * 8;
;                 const f32x4* tp = (const f32x4*)(rope_ + ((ax ? (tpos & 63) : (tpos >> 6)) * 32 + dd * 16 + hi_ * 8) * 2);
	v_and_b32_e32 v58, 0xffffffc0, v164
	v_pk_fma_f32 v[56:57], v[80:81], v[80:81], v[56:57]
	v_lshlrev_b32_e32 v79, 16, v97
	v_lshlrev_b32_e32 v78, 16, v59
	v_add_u32_e32 v58, v165, v58
	v_pk_fma_f32 v[94:95], v[78:79], v[78:79], v[56:57]
	v_and_b32_e32 v57, 0xffff0000, v97
	v_and_b32_e32 v56, 0xffff0000, v59
	v_ashrrev_i32_e32 v59, 31, v58
	v_pk_fma_f32 v[96:97], v[56:57], v[56:57], v[94:95]
	v_and_b32_e32 v95, 48, v188
	v_lshl_add_u64 v[58:59], v[58:59], 2, s[6:7]
	v_or3_b32 v94, v107, v93, v95
	flat_load_dwordx4 v[106:109], v[58:59]
	flat_load_dwordx4 v[110:113], v[58:59] offset:16
	flat_load_dwordx4 v[114:117], v[58:59] offset:32
	flat_load_dwordx4 v[118:121], v[58:59] offset:48
	v_lshlrev_b32_e32 v130, 16, v46
	v_and_b32_e32 v43, 0xffff0000, v42
	v_and_b32_e32 v42, 0xffff0000, v46
	v_lshlrev_b32_e32 v46, 16, v45
	v_and_b32_e32 v136, 0xffff0000, v45
	v_and_b32_e32 v45, 0xffff0000, v40
	v_and_b32_e32 v151, 0xffff0000, v32
	v_lshlrev_b32_e32 v139, 16, v40
	v_lshlrev_b32_e32 v149, 16, v32
	v_mov_b32_e32 v160, v45
	v_mov_b32_e32 v161, v151
	v_lshlrev_b32_e32 v124, 16, v47
	v_and_b32_e32 v128, 0xffff0000, v47
	v_lshlrev_b32_e32 v47, 16, v41
	v_lshlrev_b32_e32 v138, 16, v44
	v_and_b32_e32 v44, 0xffff0000, v44
	v_lshlrev_b32_e32 v145, 16, v33
	v_and_b32_e32 v150, 0xffff0000, v36
	v_mov_b32_e32 v158, v139
	v_mov_b32_e32 v159, v149
	v_pk_mul_f32 v[160:161], v[160:161], v[160:161]
	v_and_b32_e32 v137, 0xffff0000, v41
	v_and_b32_e32 v147, 0xffff0000, v33
	v_lshlrev_b32_e32 v148, 16, v36
	v_mov_b32_e32 v154, v47
	v_mov_b32_e32 v155, v145
	v_pk_fma_f32 v[158:159], v[158:159], v[158:159], v[160:161]
	v_mov_b32_e32 v162, v44
	v_mov_b32_e32 v163, v150
	v_lshlrev_b32_e32 v143, 16, v34
	v_lshlrev_b32_e32 v144, 16, v37
	v_mov_b32_e32 v156, v137
	v_mov_b32_e32 v157, v147
	v_pk_fma_f32 v[154:155], v[154:155], v[154:155], v[158:159]
	v_mov_b32_e32 v160, v138
	v_mov_b32_e32 v161, v148
	v_pk_mul_f32 v[162:163], v[162:163], v[162:163]
	v_lshlrev_b32_e32 v140, 16, v39
	v_and_b32_e32 v40, 0xffff0000, v39
	v_and_b32_e32 v39, 0xffff0000, v34
	v_and_b32_e32 v146, 0xffff0000, v37
	v_mov_b32_e32 v36, v131
	v_mov_b32_e32 v37, v143
	v_pk_fma_f32 v[154:155], v[156:157], v[156:157], v[154:155]
	v_mov_b32_e32 v156, v46
	v_mov_b32_e32 v157, v144
	v_pk_fma_f32 v[160:161], v[160:161], v[160:161], v[162:163]
	v_lshlrev_b32_e32 v141, 16, v35
	v_lshlrev_b32_e32 v142, 16, v38
	v_mov_b32_e32 v152, v43
	v_mov_b32_e32 v153, v39
	v_pk_fma_f32 v[36:37], v[36:37], v[36:37], v[154:155]
	v_mov_b32_e32 v158, v136
	v_mov_b32_e32 v159, v146
	v_pk_fma_f32 v[156:157], v[156:157], v[156:157], v[160:161]
	v_and_b32_e32 v41, 0xffff0000, v35
	v_and_b32_e32 v38, 0xffff0000, v38
	v_mov_b32_e32 v32, v125
	v_mov_b32_e32 v33, v141
	v_pk_fma_f32 v[36:37], v[152:153], v[152:153], v[36:37]
	v_mov_b32_e32 v152, v130
	v_mov_b32_e32 v153, v142
	v_pk_fma_f32 v[156:157], v[158:159], v[158:159], v[156:157]
	v_mov_b32_e32 v34, v129
	v_mov_b32_e32 v35, v41
	v_pk_fma_f32 v[32:33], v[32:33], v[32:33], v[36:37]
	v_mov_b32_e32 v154, v42
	v_mov_b32_e32 v155, v38
	v_pk_fma_f32 v[152:153], v[152:153], v[152:153], v[156:157]
	v_pk_fma_f32 v[32:33], v[34:35], v[34:35], v[32:33]
	v_mov_b32_e32 v34, v124
	v_mov_b32_e32 v35, v140
	v_pk_fma_f32 v[152:153], v[154:155], v[154:155], v[152:153]
	v_mov_b32_e32 v36, v128
	v_mov_b32_e32 v37, v40
	v_pk_fma_f32 v[34:35], v[34:35], v[34:35], v[152:153]
	v_add_f32_e32 v32, v32, v33
	v_pk_fma_f32 v[34:35], v[36:37], v[36:37], v[34:35]
	s_waitcnt lgkmcnt(0)
	v_mov_b32_e32 v134, v100
	v_add_f32_e32 v32, v32, v34
	v_add_f32_e32 v32, v32, v35
	v_add_f32_e32 v32, v32, v122
	v_add_f32_e32 v32, v32, v123
	v_add_f32_e32 v32, v32, v96
	v_add_f32_e32 v32, v32, v97
	ds_bpermute_b32 v33, v135, v32
	v_mov_b32_e32 v34, v98
	v_mov_b32_e32 v35, v52
	v_mov_b32_e32 v52, v99
	v_mov_b32_e32 v135, v54
	s_waitcnt lgkmcnt(0)
	v_add_f32_e32 v32, v32, v33
	v_fmamk_f32 v32, v32, 0x3c000000, v196
	v_mul_f32_e32 v33, 0x4b800000, v32
	v_cmp_gt_f32_e32 vcc, s34, v32
	v_mov_b32_e32 v54, v101
	v_mov_b32_e32 v132, v102
	v_cndmask_b32_e32 v32, v32, v33, vcc
	v_rsq_f32_e32 v32, v32
	v_mov_b32_e32 v133, v48
	v_mov_b32_e32 v48, v103
	v_mov_b32_e32 v126, v104
	v_mul_f32_e32 v33, 0x45800000, v32
	v_cndmask_b32_e32 v32, v32, v33, vcc
	v_mul_f32_e32 v32, 0x3e0293ee, v32
	v_pk_mul_f32 v[36:37], v[32:33], v[138:139] op_sel_hi:[0,1]
	v_pk_mul_f32 v[34:35], v[34:35], v[36:37]
	v_mov_b32_e32 v127, v50
	s_waitcnt vmcnt(0)
; __device__ __forceinline__ unsigned cvt_pk(float lo, float hi) { unsigned r; asm volatile("v_cvt_pk_bf16_f32 %0, %1, %2" : "=v"(r) : "v"(lo), "v"(hi)); return r; }
; __device__ __forceinline__ float bflo(unsigned w) { return __uint_as_float(w << 16); }
; __device__ __forceinline__ float bfhi(unsigned w) { return __uint_as_float(w & 0xffff0000u); }
; __device__ __forceinline__ void attn_body(const bf16_t* __restrict__ Qb, const bf16_t* __restrict__ Kh, const bf16_t* __restrict__ Vh, const bf16_t* __restrict__ Zb, ...
;     ...
; #pragma unroll
;         for (int ax = 0; ax < 2; ++ax)
; #pragma unroll
;             for (int dd = 0; dd < 2; ++dd) { const int da = ax * 4 + dd, db = da + 2;
;                 const u32x4 wa = *reinterpret_cast<const u32x4*>(&qr[da]), wb = *reinterpret_cast<const u32x4*>(&qr[db]);
;                 float xa[8] = {bflo(wa.x), bfhi(wa.x), bflo(wa.y), bfhi(wa.y), bflo(wa.z), bfhi(wa.z), bflo(wa.w), bfhi(wa.w)};
;                 float xb[8] = {bflo(wb.x), bfhi(wb.x), bflo(wb.y), bfhi(wb.y), bflo(wb.z), bfhi(wb.z), bflo(wb.w), bfhi(wb.w)};
;                 const float* ga = qg_ + da * 16 + hi_ * 8; const float* gb = qg_ + db * 16 + hi_ * 8;
;                 const f32x4* tp = (const f32x4*)(rope_ + ((ax ? (tpos & 63) : (tpos >> 6)) * 32 + dd * 16 + hi_ * 8) * 2);
;                 const f32x4 t0 = tp[0], t1 = tp[1], t2 = tp[2], t3 = tp[3];
;                 const float csv[8] = {t0[0], t0[2], t1[0], t1[2], t2[0], t2[2], t3[0], t3[2]}, snv[8] = {t0[1], t0[3], t1[1], t1[3], t2[1], t2[3], t3[1], t3[3]};
; #pragma unroll
;                 for (int e = 0; e < 8; ++e) { const float x1 = xa[e] * rinv * ga[e], x2 = xb[e] * rinv * gb[e];
;                     xa[e] = x1 * csv[e] - x2 * snv[e]; xb[e] = x2 * csv[e] + x1 * snv[e]; }
;                 u32x4 oa, ob; oa.x = cvt_pk(xa[0], xa[1]); oa.y = cvt_pk(xa[2], xa[3]); oa.z = cvt_pk(xa[4], xa[5]); oa.w = cvt_pk(xa[6], xa[7]);
;                 ob.x = cvt_pk(xb[0], xb[1]); ob.y = cvt_pk(xb[2], xb[3]); ob.z = cvt_pk(xb[4], xb[5]); ob.w = cvt_pk(xb[6], xb[7]);
;                 qr[da] = *reinterpret_cast<bf16x8*>(&oa); qr[db] = *reinterpret_cast<bf16x8*>(&ob);
;                 __builtin_amdgcn_sched_barrier(0); }
	v_pk_mul_f32 v[36:37], v[106:107], v[34:35] op_sel:[0,1] op_sel_hi:[1,0]
	v_pk_mul_f32 v[34:35], v[106:107], v[34:35]
	v_sub_f32_e32 v33, v36, v37
	v_add_f32_e32 v96, v34, v35
	v_pk_mul_f32 v[34:35], v[32:33], v[44:45] op_sel_hi:[0,1]
	v_pk_mul_f32 v[34:35], v[52:53], v[34:35]
	v_mov_b32_e32 v50, v105
	v_pk_mul_f32 v[36:37], v[108:109], v[34:35] op_sel:[0,1] op_sel_hi:[1,0]
	v_pk_mul_f32 v[34:35], v[108:109], v[34:35]
	v_sub_f32_e32 v44, v36, v37
	v_add_f32_e32 v45, v34, v35
	v_pk_mul_f32 v[34:35], v[32:33], v[46:47] op_sel_hi:[0,1]
	v_pk_mul_f32 v[34:35], v[34:35], v[134:135]
	v_readlane_b32 s53, v254, 36
	v_pk_mul_f32 v[36:37], v[110:111], v[34:35] op_sel:[0,1] op_sel_hi:[1,0]
	v_pk_mul_f32 v[34:35], v[110:111], v[34:35]
	v_sub_f32_e32 v46, v36, v37
	v_add_f32_e32 v47, v34, v35
	v_pk_mul_f32 v[34:35], v[32:33], v[136:137] op_sel_hi:[0,1]
	v_pk_mul_f32 v[34:35], v[34:35], v[54:55]
	v_readlane_b32 s54, v254, 37
	v_pk_mul_f32 v[36:37], v[112:113], v[34:35] op_sel:[0,1] op_sel_hi:[1,0]
	v_pk_mul_f32 v[34:35], v[112:113], v[34:35]
	v_sub_f32_e32 v52, v36, v37
	v_add_f32_e32 v53, v35, v34
	v_pk_mul_f32 v[34:35], v[32:33], v[130:131] op_sel_hi:[0,1]
	v_pk_mul_f32 v[34:35], v[34:35], v[132:133]
	v_readlane_b32 s55, v254, 38
	v_pk_mul_f32 v[36:37], v[114:115], v[34:35] op_sel:[0,1] op_sel_hi:[1,0]
	v_pk_mul_f32 v[34:35], v[114:115], v[34:35]
	v_sub_f32_e32 v54, v36, v37
	v_add_f32_e32 v55, v35, v34
	v_pk_mul_f32 v[34:35], v[32:33], v[42:43] op_sel_hi:[0,1]
	v_pk_mul_f32 v[34:35], v[34:35], v[48:49]
	v_readlane_b32 s56, v254, 39
	v_pk_mul_f32 v[36:37], v[116:117], v[34:35] op_sel:[0,1] op_sel_hi:[1,0]
	v_pk_mul_f32 v[34:35], v[116:117], v[34:35]
	v_sub_f32_e32 v42, v36, v37
	v_add_f32_e32 v43, v35, v34
	v_pk_mul_f32 v[34:35], v[32:33], v[124:125] op_sel_hi:[0,1]
	v_pk_mul_f32 v[34:35], v[34:35], v[126:127]
	v_readlane_b32 s57, v254, 40
	v_pk_mul_f32 v[36:37], v[118:119], v[34:35] op_sel:[0,1] op_sel_hi:[1,0]
	v_pk_mul_f32 v[34:35], v[118:119], v[34:35]
	v_sub_f32_e32 v48, v36, v37
	v_add_f32_e32 v49, v35, v34
	v_pk_mul_f32 v[34:35], v[32:33], v[128:129] op_sel_hi:[0,1]
	v_pk_mul_f32 v[34:35], v[34:35], v[50:51]
	v_cvt_pk_bf16_f32 v116, v33, v44
	v_cvt_pk_bf16_f32 v117, v46, v52
	v_cvt_pk_bf16_f32 v118, v54, v42
	s_nop 0
	v_pk_mul_f32 v[36:37], v[120:121], v[34:35] op_sel:[0,1] op_sel_hi:[1,0]
	v_pk_mul_f32 v[34:35], v[120:121], v[34:35]
	v_sub_f32_e32 v36, v36, v37
	v_add_f32_e32 v34, v35, v34
	v_cvt_pk_bf16_f32 v119, v48, v36
	v_cvt_pk_bf16_f32 v112, v96, v45
	v_cvt_pk_bf16_f32 v113, v47, v53
	v_cvt_pk_bf16_f32 v114, v55, v43
	v_cvt_pk_bf16_f32 v115, v49, v34
	flat_load_dwordx4 v[34:37], v[68:69] offset:192
	flat_load_dwordx4 v[42:45], v[68:69] offset:64
	flat_load_dwordx4 v[46:49], v[68:69] offset:208
	flat_load_dwordx4 v[50:53], v[68:69] offset:80
	flat_load_dwordx4 v[96:99], v[58:59] offset:128
	flat_load_dwordx4 v[100:103], v[58:59] offset:144
	flat_load_dwordx4 v[104:107], v[58:59] offset:160
	flat_load_dwordx4 v[108:111], v[58:59] offset:176
	v_pk_mul_f32 v[54:55], v[32:33], v[148:149] op_sel_hi:[0,1]
	v_pk_mul_f32 v[58:59], v[32:33], v[150:151] op_sel_hi:[0,1]
	v_pk_mul_f32 v[120:121], v[32:33], v[144:145] op_sel_hi:[0,1]
	v_pk_mul_f32 v[122:123], v[32:33], v[146:147] op_sel_hi:[0,1]
	v_pk_mul_f32 v[124:125], v[32:33], v[142:143] op_sel_hi:[0,1]
	v_pk_mul_f32 v[38:39], v[32:33], v[38:39] op_sel_hi:[0,1]
	v_pk_mul_f32 v[126:127], v[32:33], v[140:141] op_sel_hi:[0,1]
	v_pk_mul_f32 v[40:41], v[32:33], v[40:41] op_sel_hi:[0,1]
	s_waitcnt vmcnt(0) lgkmcnt(0)
	v_mov_b32_e32 v128, v34
	v_mov_b32_e32 v129, v42
	v_mov_b32_e32 v42, v35
	v_mov_b32_e32 v34, v36
	v_mov_b32_e32 v35, v44
	v_mov_b32_e32 v44, v37
	v_mov_b32_e32 v36, v46
	v_mov_b32_e32 v37, v50
	v_mov_b32_e32 v50, v47
	v_mov_b32_e32 v46, v48
	v_mov_b32_e32 v47, v52
	v_mov_b32_e32 v52, v49
	v_pk_mul_f32 v[48:49], v[54:55], v[128:129]
	v_pk_mul_f32 v[42:43], v[58:59], v[42:43]
	v_pk_mul_f32 v[34:35], v[120:121], v[34:35]
	v_pk_mul_f32 v[44:45], v[122:123], v[44:45]
	v_pk_mul_f32 v[36:37], v[124:125], v[36:37]
	v_pk_mul_f32 v[38:39], v[38:39], v[50:51]
	v_pk_mul_f32 v[46:47], v[126:127], v[46:47]
	v_pk_mul_f32 v[40:41], v[40:41], v[52:53]
	v_pk_mul_f32 v[50:51], v[96:97], v[48:49] op_sel:[0,1] op_sel_hi:[1,0]
	v_pk_mul_f32 v[48:49], v[96:97], v[48:49]
	v_pk_mul_f32 v[52:53], v[98:99], v[42:43] op_sel:[0,1] op_sel_hi:[1,0]
	v_pk_mul_f32 v[42:43], v[98:99], v[42:43]
	v_pk_mul_f32 v[54:55], v[100:101], v[34:35] op_sel:[0,1] op_sel_hi:[1,0]
	v_pk_mul_f32 v[34:35], v[100:101], v[34:35]
	v_pk_mul_f32 v[58:59], v[102:103], v[44:45] op_sel:[0,1] op_sel_hi:[1,0]
	v_pk_mul_f32 v[44:45], v[102:103], v[44:45]
	v_pk_mul_f32 v[96:97], v[104:105], v[36:37] op_sel:[0,1] op_sel_hi:[1,0]
	v_pk_mul_f32 v[36:37], v[104:105], v[36:37]
	v_pk_mul_f32 v[98:99], v[106:107], v[38:39] op_sel:[0,1] op_sel_hi:[1,0]
	v_pk_mul_f32 v[38:39], v[106:107], v[38:39]
	v_pk_mul_f32 v[100:101], v[108:109], v[46:47] op_sel:[0,1] op_sel_hi:[1,0]
	v_pk_mul_f32 v[46:47], v[108:109], v[46:47]
	v_pk_mul_f32 v[102:103], v[110:111], v[40:41] op_sel:[0,1] op_sel_hi:[1,0]
	v_pk_mul_f32 v[40:41], v[110:111], v[40:41]
	v_sub_f32_e32 v33, v50, v51
	v_add_f32_e32 v48, v49, v48
	v_sub_f32_e32 v49, v52, v53
	v_add_f32_e32 v42, v43, v42
	v_sub_f32_e32 v43, v54, v55
	v_add_f32_e32 v34, v35, v34
	v_sub_f32_e32 v35, v58, v59
	v_add_f32_e32 v44, v45, v44
	v_sub_f32_e32 v45, v96, v97
	v_add_f32_e32 v36, v37, v36
	v_sub_f32_e32 v37, v98, v99
	v_add_f32_e32 v38, v39, v38
	v_sub_f32_e32 v39, v100, v101
	v_add_f32_e32 v46, v47, v46
	v_sub_f32_e32 v47, v102, v103
	v_add_f32_e32 v40, v41, v40
	v_cvt_pk_bf16_f32 v124, v33, v49
	v_cvt_pk_bf16_f32 v125, v43, v35
; __device__ __forceinline__ unsigned cvt_pk(float lo, float hi) { unsigned r; asm volatile("v_cvt_pk_bf16_f32 %0, %1, %2" : "=v"(r) : "v"(lo), "v"(hi)); return r; }
; __device__ __forceinline__ float bflo(unsigned w) { return __uint_as_float(w << 16); }
; __device__ __forceinline__ float bfhi(unsigned w) { return __uint_as_float(w & 0xffff0000u); }
; __device__ __forceinline__ void attn_body(const bf16_t* __restrict__ Qb, const bf16_t* __restrict__ Kh, const bf16_t* __restrict__ Vh, const bf16_t* __restrict__ Zb, ...
;     ...
; #pragma unroll
;         for (int ax = 0; ax < 2; ++ax)
; #pragma unroll
;             for (int dd = 0; dd < 2; ++dd) { const int da = ax * 4 + dd, db = da + 2;
;                 const u32x4 wa = *reinterpret_cast<const u32x4*>(&qr[da]), wb = *reinterpret_cast<const u32x4*>(&qr[db]);
;                 float xa[8] = {bflo(wa.x), bfhi(wa.x), bflo(wa.y), bfhi(wa.y), bflo(wa.z), bfhi(wa.z), bflo(wa.w), bfhi(wa.w)};
;                 float xb[8] = {bflo(wb.x), bfhi(wb.x), bflo(wb.y), bfhi(wb.y), bflo(wb.z), bfhi(wb.z), bflo(wb.w), bfhi(wb.w)};
;                 const float* ga = qg_ + da * 16 + hi_ * 8; const float* gb = qg_ + db * 16 + hi_ * 8;
;                 const f32x4* tp = (const f32x4*)(rope_ + ((ax ? (tpos & 63) : (tpos >> 6)) * 32 + dd * 16 + hi_ * 8) * 2);
;                 const f32x4 t0 = tp[0], t1 = tp[1], t2 = tp[2], t3 = tp[3];
;                 const float csv[8] = {t0[0], t0[2], t1[0], t1[2], t2[0], t2[2], t3[0], t3[2]}, snv[8] = {t0[1], t0[3], t1[1], t1[3], t2[1], t2[3], t3[1], t3[3]};
; #pragma unroll
;                 for (int e = 0; e < 8; ++e) { const float x1 = xa[e] * rinv * ga[e], x2 = xb[e] * rinv * gb[e];
;                     xa[e] = x1 * csv[e] - x2 * snv[e]; xb[e] = x2 * csv[e] + x1 * snv[e]; }
;                 u32x4 oa, ob; oa.x = cvt_pk(xa[0], xa[1]); oa.y = cvt_pk(xa[2], xa[3]); oa.z = cvt_pk(xa[4], xa[5]); oa.w = cvt_pk(xa[6], xa[7]);
;                 ob.x = cvt_pk(xb[0], xb[1]); ob.y = cvt_pk(xb[2], xb[3]); ob.z = cvt_pk(xb[4], xb[5]); ob.w = cvt_pk(xb[6], xb[7]);
;                 qr[da] = *reinterpret_cast<bf16x8*>(&oa); qr[db] = *reinterpret_cast<bf16x8*>(&ob);
;                 __builtin_amdgcn_sched_barrier(0); }
	v_cvt_pk_bf16_f32 v126, v45, v37
	v_cvt_pk_bf16_f32 v127, v39, v47
	v_cvt_pk_bf16_f32 v120, v48, v42
	v_cvt_pk_bf16_f32 v121, v34, v44
	v_cvt_pk_bf16_f32 v122, v36, v38
	v_cvt_pk_bf16_f32 v123, v46, v40
	v_lshlrev_b32_e32 v33, 6, v164
	v_and_b32_e32 v33, 0xfc0, v33
	v_add_u32_e32 v50, v165, v33
	flat_load_dwordx4 v[34:37], v[68:69] offset:384
	flat_load_dwordx4 v[38:41], v[68:69] offset:256
	flat_load_dwordx4 v[42:45], v[68:69] offset:400
	flat_load_dwordx4 v[46:49], v[68:69] offset:272
	v_ashrrev_i32_e32 v51, 31, v50
	v_lshl_add_u64 v[54:55], v[50:51], 2, s[6:7]
	flat_load_dwordx4 v[50:53], v[54:55]
	flat_load_dwordx4 v[96:99], v[54:55] offset:16
	flat_load_dwordx4 v[100:103], v[54:55] offset:32
	flat_load_dwordx4 v[104:107], v[54:55] offset:48
	v_mov_b32_e32 v58, v82
	v_mov_b32_e32 v59, v60
	v_mov_b32_e32 v108, v84
	v_mov_b32_e32 v109, v62
	v_mov_b32_e32 v110, v86
	v_mov_b32_e32 v111, v64
	v_mov_b32_e32 v128, v88
	v_mov_b32_e32 v129, v66
	v_mov_b32_e32 v130, v90
	v_mov_b32_e32 v131, v70
	v_mov_b32_e32 v132, v80
	v_mov_b32_e32 v133, v72
	v_mov_b32_e32 v134, v78
	v_mov_b32_e32 v135, v74
	v_mov_b32_e32 v136, v56
	v_mov_b32_e32 v137, v76
	v_pk_mul_f32 v[58:59], v[32:33], v[58:59] op_sel_hi:[0,1]
	v_pk_mul_f32 v[108:109], v[32:33], v[108:109] op_sel_hi:[0,1]
	v_pk_mul_f32 v[110:111], v[32:33], v[110:111] op_sel_hi:[0,1]
	v_pk_mul_f32 v[128:129], v[32:33], v[128:129] op_sel_hi:[0,1]
	v_pk_mul_f32 v[130:131], v[32:33], v[130:131] op_sel_hi:[0,1]
	v_pk_mul_f32 v[132:133], v[32:33], v[132:133] op_sel_hi:[0,1]
	v_pk_mul_f32 v[134:135], v[32:33], v[134:135] op_sel_hi:[0,1]
	v_pk_mul_f32 v[136:137], v[32:33], v[136:137] op_sel_hi:[0,1]
	s_waitcnt vmcnt(0) lgkmcnt(0)
	v_mov_b32_e32 v138, v34
	v_mov_b32_e32 v139, v38
	v_mov_b32_e32 v38, v35
	v_mov_b32_e32 v34, v36
	v_mov_b32_e32 v35, v40
	v_mov_b32_e32 v40, v37
	v_mov_b32_e32 v36, v42
	v_mov_b32_e32 v37, v46
	v_mov_b32_e32 v46, v43
	v_mov_b32_e32 v42, v44
	v_mov_b32_e32 v43, v48
	v_mov_b32_e32 v48, v45
	v_pk_mul_f32 v[44:45], v[58:59], v[138:139]
	v_pk_mul_f32 v[38:39], v[108:109], v[38:39]
	v_pk_mul_f32 v[34:35], v[110:111], v[34:35]
	v_pk_mul_f32 v[40:41], v[128:129], v[40:41]
	v_pk_mul_f32 v[36:37], v[130:131], v[36:37]
	v_pk_mul_f32 v[46:47], v[132:133], v[46:47]
	v_pk_mul_f32 v[42:43], v[134:135], v[42:43]
	v_pk_mul_f32 v[48:49], v[136:137], v[48:49]
	v_pk_mul_f32 v[58:59], v[50:51], v[44:45] op_sel:[0,1] op_sel_hi:[1,0]
	v_pk_mul_f32 v[44:45], v[50:51], v[44:45]
	v_pk_mul_f32 v[50:51], v[52:53], v[38:39] op_sel:[0,1] op_sel_hi:[1,0]
	v_pk_mul_f32 v[38:39], v[52:53], v[38:39]
	v_pk_mul_f32 v[52:53], v[96:97], v[34:35] op_sel:[0,1] op_sel_hi:[1,0]
	v_pk_mul_f32 v[34:35], v[96:97], v[34:35]
	v_pk_mul_f32 v[96:97], v[98:99], v[40:41] op_sel:[0,1] op_sel_hi:[1,0]
	v_pk_mul_f32 v[40:41], v[98:99], v[40:41]
	v_pk_mul_f32 v[98:99], v[100:101], v[36:37] op_sel:[0,1] op_sel_hi:[1,0]
	v_pk_mul_f32 v[36:37], v[100:101], v[36:37]
	v_pk_mul_f32 v[100:101], v[102:103], v[46:47] op_sel:[0,1] op_sel_hi:[1,0]
	v_pk_mul_f32 v[46:47], v[102:103], v[46:47]
	v_pk_mul_f32 v[102:103], v[104:105], v[42:43] op_sel:[0,1] op_sel_hi:[1,0]
	v_pk_mul_f32 v[42:43], v[104:105], v[42:43]
	v_pk_mul_f32 v[104:105], v[106:107], v[48:49] op_sel:[0,1] op_sel_hi:[1,0]
	v_add_f32_e32 v44, v45, v44
	v_sub_f32_e32 v45, v50, v51
	v_add_f32_e32 v50, v35, v34
	v_pk_mul_f32 v[34:35], v[106:107], v[48:49]
	v_sub_f32_e32 v33, v58, v59
	v_add_f32_e32 v38, v39, v38
	v_sub_f32_e32 v39, v52, v53
	v_sub_f32_e32 v51, v96, v97
	v_add_f32_e32 v40, v41, v40
	v_sub_f32_e32 v41, v98, v99
	v_add_f32_e32 v36, v37, v36
	v_sub_f32_e32 v37, v100, v101
	v_add_f32_e32 v46, v47, v46
	v_sub_f32_e32 v47, v102, v103
	v_add_f32_e32 v42, v43, v42
	v_sub_f32_e32 v43, v104, v105
	v_add_f32_e32 v34, v35, v34
	v_cvt_pk_bf16_f32 v132, v33, v45
	v_cvt_pk_bf16_f32 v133, v39, v51
	v_cvt_pk_bf16_f32 v134, v41, v37
	v_cvt_pk_bf16_f32 v135, v47, v43
	v_cvt_pk_bf16_f32 v128, v44, v38
	v_cvt_pk_bf16_f32 v129, v50, v40
	v_cvt_pk_bf16_f32 v130, v36, v46
	v_cvt_pk_bf16_f32 v131, v42, v34
	flat_load_dwordx4 v[34:37], v[68:69] offset:448
	flat_load_dwordx4 v[38:41], v[68:69] offset:320
	flat_load_dwordx4 v[42:45], v[68:69] offset:464
	flat_load_dwordx4 v[46:49], v[68:69] offset:336
	flat_load_dwordx4 v[50:53], v[54:55] offset:128
	flat_load_dwordx4 v[96:99], v[54:55] offset:144
	flat_load_dwordx4 v[100:103], v[54:55] offset:160
	flat_load_dwordx4 v[104:107], v[54:55] offset:176
	v_mov_b32_e32 v60, v83
	v_mov_b32_e32 v62, v85
	v_mov_b32_e32 v64, v87
	v_mov_b32_e32 v66, v89
	v_mov_b32_e32 v70, v91
	v_mov_b32_e32 v72, v81
	v_mov_b32_e32 v74, v79
	v_mov_b32_e32 v76, v57
	v_pk_mul_f32 v[54:55], v[32:33], v[60:61] op_sel_hi:[0,1]
	v_pk_mul_f32 v[56:57], v[32:33], v[62:63] op_sel_hi:[0,1]
	v_pk_mul_f32 v[58:59], v[32:33], v[64:65] op_sel_hi:[0,1]
	v_pk_mul_f32 v[60:61], v[32:33], v[66:67] op_sel_hi:[0,1]
	v_pk_mul_f32 v[62:63], v[32:33], v[70:71] op_sel_hi:[0,1]
	v_pk_mul_f32 v[64:65], v[32:33], v[72:73] op_sel_hi:[0,1]
	v_pk_mul_f32 v[66:67], v[32:33], v[74:75] op_sel_hi:[0,1]
	v_pk_mul_f32 v[32:33], v[32:33], v[76:77] op_sel_hi:[0,1]
	s_waitcnt vmcnt(0) lgkmcnt(0)
; #define SWRITE(b, i) do { *(bf16x8*)((char*)V_lds + (b) * SHM_V + vst0) = sr_[i].vs0;          \
;     *(bf16x8*)((char*)V_lds + (b) * SHM_V + vst1) = sr_[i].vs1; int kc = sc * 2;               \
;     *(bf16x8*)((char*)K_lds + (b) * SHM_K + KSWZ(sr, kc)) = sr_[i].ks0;                       \
;     *(bf16x8*)((char*)K_lds + (b) * SHM_K + KSWZ(32 + sr, kc)) = sr_[i].ks1; } while (0)
; __device__ __forceinline__ void qkt(f32x16& p0, f32x16& p1, const bf16_t* Ks, const bf16x8* qr, int r32, int hi) {
;     p0 = f32x16{}; p1 = f32x16{};
;     for (int d0 = 0; d0 < 8; ++d0) { int cb = (d0 * 16 + hi * 8) * 2;
;         bf16x8 b0 = *reinterpret_cast<const bf16x8*>((const char*)Ks + KSWZ(r32, cb));
;         bf16x8 b1 = *reinterpret_cast<const bf16x8*>((const char*)Ks + KSWZ(32 + r32, cb));
;         p0 = __builtin_amdgcn_mfma_f32_32x32x16_bf16(b0, qr[d0], p0, 0, 0, 0);
;         p1 = __builtin_amdgcn_mfma_f32_32x32x16_bf16(b1, qr[d0], p1, 0, 0, 0); }
; }
; __device__ __forceinline__ void attn_body(const bf16_t* __restrict__ Qb, const bf16_t* __restrict__ Kh, const bf16_t* __restrict__ Vh, const bf16_t* __restrict__ Zb, ...
;     ...
;     f32x16 pA0, pA1, pB0, pB1; bf16x8 pa0, pa1, pa2, pa3; const int NT = seq / KVBLK;
;     constexpr int SE = 0, SO = 1;
;     asm volatile("s_waitcnt vmcnt(0)" ::: "memory"); SWRITE(0, SE); __syncthreads();
;     qkt(pA0, pA1, K_lds, qr, r32, hi); partialSM(pA0, pA1, negBC);
	v_mov_b32_e32 v68, v34
	v_mov_b32_e32 v69, v38
	v_mov_b32_e32 v38, v35
	v_mov_b32_e32 v34, v36
	v_mov_b32_e32 v35, v40
	v_mov_b32_e32 v40, v37
	v_mov_b32_e32 v36, v42
	v_mov_b32_e32 v37, v46
	v_mov_b32_e32 v46, v43
	v_mov_b32_e32 v42, v44
	v_mov_b32_e32 v43, v48
	v_mov_b32_e32 v48, v45
	v_pk_mul_f32 v[44:45], v[54:55], v[68:69]
	v_pk_mul_f32 v[38:39], v[56:57], v[38:39]
	v_pk_mul_f32 v[34:35], v[58:59], v[34:35]
	v_pk_mul_f32 v[40:41], v[60:61], v[40:41]
	v_pk_mul_f32 v[36:37], v[62:63], v[36:37]
	v_pk_mul_f32 v[46:47], v[64:65], v[46:47]
	v_pk_mul_f32 v[42:43], v[66:67], v[42:43]
	v_pk_mul_f32 v[32:33], v[32:33], v[48:49]
	v_pk_mul_f32 v[48:49], v[50:51], v[44:45] op_sel:[0,1] op_sel_hi:[1,0]
	v_pk_mul_f32 v[44:45], v[50:51], v[44:45]
	v_pk_mul_f32 v[50:51], v[52:53], v[38:39] op_sel:[0,1] op_sel_hi:[1,0]
	v_pk_mul_f32 v[38:39], v[52:53], v[38:39]
	v_pk_mul_f32 v[52:53], v[96:97], v[34:35] op_sel:[0,1] op_sel_hi:[1,0]
	v_pk_mul_f32 v[34:35], v[96:97], v[34:35]
	v_pk_mul_f32 v[54:55], v[98:99], v[40:41] op_sel:[0,1] op_sel_hi:[1,0]
	v_pk_mul_f32 v[40:41], v[98:99], v[40:41]
	v_pk_mul_f32 v[56:57], v[100:101], v[36:37] op_sel:[0,1] op_sel_hi:[1,0]
	v_pk_mul_f32 v[36:37], v[100:101], v[36:37]
	v_pk_mul_f32 v[58:59], v[102:103], v[46:47] op_sel:[0,1] op_sel_hi:[1,0]
	v_pk_mul_f32 v[46:47], v[102:103], v[46:47]
	v_pk_mul_f32 v[60:61], v[104:105], v[42:43] op_sel:[0,1] op_sel_hi:[1,0]
	v_pk_mul_f32 v[42:43], v[104:105], v[42:43]
	v_pk_mul_f32 v[62:63], v[106:107], v[32:33] op_sel:[0,1] op_sel_hi:[1,0]
	v_pk_mul_f32 v[32:33], v[106:107], v[32:33]
	v_sub_f32_e32 v48, v48, v49
	v_add_f32_e32 v44, v45, v44
	v_sub_f32_e32 v45, v50, v51
	v_add_f32_e32 v38, v39, v38
	v_sub_f32_e32 v39, v52, v53
	v_add_f32_e32 v34, v35, v34
	v_sub_f32_e32 v35, v54, v55
	v_add_f32_e32 v40, v41, v40
	v_sub_f32_e32 v41, v56, v57
	v_add_f32_e32 v36, v37, v36
	v_sub_f32_e32 v37, v58, v59
	v_add_f32_e32 v46, v47, v46
	v_sub_f32_e32 v47, v60, v61
	v_add_f32_e32 v42, v43, v42
	v_sub_f32_e32 v43, v62, v63
	v_add_f32_e32 v32, v33, v32
	v_cvt_pk_bf16_f32 v140, v48, v45
	v_cvt_pk_bf16_f32 v141, v39, v35
	v_cvt_pk_bf16_f32 v142, v41, v37
	v_cvt_pk_bf16_f32 v143, v47, v43
	v_cvt_pk_bf16_f32 v136, v44, v38
	v_cvt_pk_bf16_f32 v137, v34, v40
	v_cvt_pk_bf16_f32 v138, v36, v46
	v_cvt_pk_bf16_f32 v139, v42, v32
	v_or3_b32 v32, v92, v93, v95
	v_lshrrev_b32_e32 v32, 7, v200
	v_lshlrev_b32_e32 v32, 11, v32
	v_bfe_u32 v33, v200, 2, 2
	v_lshl_or_b32 v32, v33, 9, v32
	v_bfe_u32 v33, v200, 4, 3
	v_lshl_or_b32 v32, v33, 6, v32
	v_and_b32_e32 v33, 3, v200
	v_lshl_or_b32 v207, v33, 4, v32
	s_waitcnt vmcnt(0)
	ds_write_b128 v207, v[8:11]
	v_lshlrev_b32_e32 v8, 8, v186
	v_and_b32_e32 v9, 0xf0, v200
	v_bitop3_b32 v8, v188, v8, v9 bitop3:0xde
	v_add_u32_e32 v208, 0x2000, v207
	v_add_u32_e32 v209, 0, v8
	ds_write_b128 v208, v[12:15]
	ds_write_b128 v209, v[4:7] offset:32768
	v_lshlrev_b32_e32 v4, 8, v189
	v_bitop3_b32 v4, v188, v4, v9 bitop3:0xde
	v_add_u32_e32 v210, 0, v4
	ds_write_b128 v210, v[0:3] offset:32768
	v_lshlrev_b32_e32 v0, 4, v200
	v_lshlrev_b32_e32 v40, 8, v201
	v_and_b32_e32 v41, 0xf0, v0
	v_bitop3_b32 v0, v184, v40, v41 bitop3:0xde
	v_add_u32_e32 v211, 0, v0
	s_waitcnt lgkmcnt(0)
	s_barrier
	ds_read_b128 v[0:3], v211 offset:32768
	ds_read_b128 v[32:35], v211 offset:40960
	s_waitcnt lgkmcnt(1)
	v_mfma_f32_32x32x16_bf16 v[0:15], v[0:3], v[116:119], 0
	v_cmp_ne_u32_e64 s[6:7], 1, v197
	s_andn2_b64 vcc, exec, s[4:5]
	s_waitcnt lgkmcnt(0)
	v_mfma_f32_32x32x16_bf16 v[64:79], v[32:35], v[116:119], 0
	v_or_b32_e32 v32, 32, v184
	v_bitop3_b32 v32, v32, v40, v41 bitop3:0xde
	v_add_u32_e32 v212, 0, v32
	ds_read_b128 v[32:35], v212 offset:32768
	ds_read_b128 v[36:39], v212 offset:40960
	s_waitcnt lgkmcnt(1)
	v_mfma_f32_32x32x16_bf16 v[0:15], v[32:35], v[124:127], v[0:15]
	v_or_b32_e32 v32, 64, v184
	v_bitop3_b32 v32, v32, v40, v41 bitop3:0xde
	v_add_u32_e32 v213, 0, v32
	s_waitcnt lgkmcnt(0)
	v_mfma_f32_32x32x16_bf16 v[64:79], v[36:39], v[124:127], v[64:79]
	ds_read_b128 v[32:35], v213 offset:32768
	ds_read_b128 v[36:39], v213 offset:40960
	s_waitcnt lgkmcnt(1)
	v_mfma_f32_32x32x16_bf16 v[0:15], v[32:35], v[112:115], v[0:15]
	v_or_b32_e32 v32, 0x60, v184
	v_bitop3_b32 v32, v32, v40, v41 bitop3:0xde
	v_add_u32_e32 v214, 0, v32
	s_waitcnt lgkmcnt(0)
	v_mfma_f32_32x32x16_bf16 v[64:79], v[36:39], v[112:115], v[64:79]
	ds_read_b128 v[32:35], v214 offset:32768
	ds_read_b128 v[36:39], v214 offset:40960
	s_waitcnt lgkmcnt(1)
	v_mfma_f32_32x32x16_bf16 v[0:15], v[32:35], v[120:123], v[0:15]
	v_or_b32_e32 v32, 0x80, v184
	v_bitop3_b32 v32, v32, v40, v41 bitop3:0xde
	v_add_u32_e32 v215, 0, v32
	s_waitcnt lgkmcnt(0)
	v_mfma_f32_32x32x16_bf16 v[64:79], v[36:39], v[120:123], v[64:79]
	ds_read_b128 v[32:35], v215 offset:32768
	ds_read_b128 v[36:39], v215 offset:40960
	s_waitcnt lgkmcnt(1)
	v_mfma_f32_32x32x16_bf16 v[0:15], v[32:35], v[132:135], v[0:15]
	v_or_b32_e32 v32, 0xa0, v184
	v_bitop3_b32 v32, v32, v40, v41 bitop3:0xde
	v_add_u32_e32 v216, 0, v32
	s_waitcnt lgkmcnt(0)
	v_mfma_f32_32x32x16_bf16 v[64:79], v[36:39], v[132:135], v[64:79]
	ds_read_b128 v[32:35], v216 offset:32768
	ds_read_b128 v[36:39], v216 offset:40960
	s_waitcnt lgkmcnt(1)
	v_mfma_f32_32x32x16_bf16 v[0:15], v[32:35], v[140:143], v[0:15]
	v_or_b32_e32 v32, 0xc0, v184
	v_bitop3_b32 v32, v32, v40, v41 bitop3:0xde
	v_add_u32_e32 v217, 0, v32
	s_waitcnt lgkmcnt(0)
	v_mfma_f32_32x32x16_bf16 v[64:79], v[36:39], v[140:143], v[64:79]
	ds_read_b128 v[32:35], v217 offset:32768
	ds_read_b128 v[36:39], v217 offset:40960
	s_waitcnt lgkmcnt(1)
	v_mfma_f32_32x32x16_bf16 v[0:15], v[32:35], v[128:131], v[0:15]
	v_or_b32_e32 v32, 0xe0, v184
	v_bitop3_b32 v32, v32, v40, v41 bitop3:0xde
	v_add_u32_e32 v218, 0, v32
	s_waitcnt lgkmcnt(0)
	v_mfma_f32_32x32x16_bf16 v[64:79], v[36:39], v[128:131], v[64:79]
	ds_read_b128 v[32:35], v218 offset:32768
	ds_read_b128 v[36:39], v218 offset:40960
	s_waitcnt lgkmcnt(1)
	v_mfma_f32_32x32x16_bf16 v[0:15], v[32:35], v[136:139], v[0:15]
	s_waitcnt lgkmcnt(0)
	v_mfma_f32_32x32x16_bf16 v[64:79], v[36:39], v[136:139], v[64:79]
	s_cbranch_vccnz .LBB0_487
	v_mov_b32_e32 v181, v180
	s_nop 7
	v_pk_add_f32 v[14:15], v[180:181], v[14:15]
	v_pk_add_f32 v[12:13], v[180:181], v[12:13]
	v_pk_add_f32 v[10:11], v[180:181], v[10:11]
	v_pk_add_f32 v[8:9], v[180:181], v[8:9]
	v_pk_add_f32 v[6:7], v[180:181], v[6:7]
	v_pk_add_f32 v[4:5], v[180:181], v[4:5]
	v_pk_add_f32 v[2:3], v[180:181], v[2:3]
	v_pk_add_f32 v[0:1], v[182:183], v[0:1]
	v_pk_add_f32 v[78:79], v[180:181], v[78:79]
	v_pk_add_f32 v[76:77], v[180:181], v[76:77]
	v_pk_add_f32 v[74:75], v[180:181], v[74:75]
	v_pk_add_f32 v[72:73], v[180:181], v[72:73]
	v_pk_add_f32 v[70:71], v[180:181], v[70:71]
	v_pk_add_f32 v[68:69], v[180:181], v[68:69]
	v_pk_add_f32 v[66:67], v[180:181], v[66:67]
	v_pk_add_f32 v[64:65], v[182:183], v[64:65]

; #define SBAR() __builtin_amdgcn_sched_barrier(0)
; #define SLOAD(i, k0) do { sr_[i].vs0 = LD8(&Vh[(long)((k0) + sr) * LDK + sc]); sr_[i].vs1 = LD8(&Vh[(long)((k0) + 32 + sr) * LDK + sc]); \
;     sr_[i].ks0 = LD8(&Kh[(long)((k0) + sr) * LDK + sc]); sr_[i].ks1 = LD8(&Kh[(long)((k0) + 32 + sr) * LDK + sc]); } while (0)
; __device__ __forceinline__ void finishSM(f32x16& p0, f32x16& p1, float alpha, float& l_reg, bf16x8& pa0, bf16x8& pa1, bf16x8& pa2, bf16x8& pa3) {
;     for (int r = 0; r < 16; ++r) p1[r] = __builtin_amdgcn_exp2f(p1[r]);
;     float ps = 0; for (int r = 0; r < 16; ++r) ps += p0[r]; for (int r = 0; r < 16; ++r) ps += p1[r];
;     { auto rr = __builtin_amdgcn_permlane32_swap(__float_as_uint(ps), __float_as_uint(ps), false, false);
;       ps = __uint_as_float(rr[0]) + __uint_as_float(rr[1]); }
;     l_reg = l_reg * alpha + ps;
;     ...
;     PK4(p0, 0, pa0); PK4(p0, 8, pa1); PK4(p1, 0, pa2); PK4(p1, 8, pa3);
;     ...
; }
; __device__ __forceinline__ void attn_body(const bf16_t* __restrict__ Qb, const bf16_t* __restrict__ Kh, const bf16_t* __restrict__ Vh, const bf16_t* __restrict__ Zb, ...
;     ...
;     for (int j = 1; j + 1 < NT; j += 2) {
;         SBAR(); qkt(pB0, pB1, (bf16_t*)((char*)K_lds + SHM_K), qr, r32, hi);
;         finishSM(pA0, pA1, 1.f, l_reg, pa0, pa1, pa2, pa3); SBAR();
;         SLOAD(SO, (j + 2) * KVBLK); SBAR();
;         pv_d0(o, vb0, pa0, pa1, pa2, pa3); partialSM(pB0, pB1, negBC);
.LBB0_490:
	ds_read_b128 v[236:239], v211 offset:49152
	ds_read_b128 v[240:243], v211 offset:57344
	ds_read_b128 v[244:247], v212 offset:49152
	ds_read_b128 v[248:251], v212 offset:57344
	v_add_f32_e32 v219, v233, v235
	v_cvt_pk_bf16_f32 v160, v233, v235
	v_add_f32_e32 v219, v231, v219
	s_waitcnt lgkmcnt(3)
	v_mfma_f32_32x32x16_bf16 v[96:111], v[236:239], v[116:119], 0
	v_cvt_pk_bf16_f32 v161, v231, v234
	v_add_f32_e32 v219, v234, v219
	v_cvt_pk_bf16_f32 v162, v230, v232
	v_add_f32_e32 v219, v230, v219
	s_waitcnt lgkmcnt(2)
	v_mfma_f32_32x32x16_bf16 v[80:95], v[240:243], v[116:119], 0
	ds_read_b128 v[236:239], v213 offset:49152
	ds_read_b128 v[240:243], v213 offset:57344
	v_cvt_pk_bf16_f32 v163, v228, v229
	v_add_f32_e32 v219, v232, v219
	v_cvt_pk_bf16_f32 v164, v225, v227
	v_add_f32_e32 v219, v228, v219
	s_waitcnt lgkmcnt(3)
	v_mfma_f32_32x32x16_bf16 v[96:111], v[244:247], v[124:127], v[96:111]
	v_cvt_pk_bf16_f32 v165, v224, v226
	v_add_f32_e32 v219, v229, v219
	v_cvt_pk_bf16_f32 v166, v221, v223
	s_waitcnt lgkmcnt(2)
	v_mfma_f32_32x32x16_bf16 v[80:95], v[248:251], v[124:127], v[80:95]
	ds_read_b128 v[244:247], v214 offset:49152
	ds_read_b128 v[248:251], v214 offset:57344
	v_add_f32_e32 v219, v225, v219
	v_cvt_pk_bf16_f32 v167, v181, v222
	v_add_f32_e32 v219, v227, v219
	s_waitcnt lgkmcnt(3)
	v_mfma_f32_32x32x16_bf16 v[96:111], v[236:239], v[112:115], v[96:111]
	v_cvt_pk_bf16_f32 v168, v64, v65
	v_add_f32_e32 v219, v224, v219
	v_cvt_pk_bf16_f32 v169, v66, v67
	s_waitcnt lgkmcnt(2)
	v_mfma_f32_32x32x16_bf16 v[80:95], v[240:243], v[112:115], v[80:95]
	ds_read_b128 v[236:239], v215 offset:49152
	ds_read_b128 v[240:243], v215 offset:57344
	v_add_f32_e32 v219, v226, v219
	v_cvt_pk_bf16_f32 v170, v68, v69
	v_add_f32_e32 v219, v221, v219
	s_waitcnt lgkmcnt(3)
	v_mfma_f32_32x32x16_bf16 v[96:111], v[244:247], v[120:123], v[96:111]
	v_cvt_pk_bf16_f32 v171, v70, v71
	v_add_f32_e32 v219, v223, v219
	v_cvt_pk_bf16_f32 v172, v72, v73
	s_waitcnt lgkmcnt(2)
	v_mfma_f32_32x32x16_bf16 v[80:95], v[248:251], v[120:123], v[80:95]
	ds_read_b128 v[244:247], v216 offset:49152
	ds_read_b128 v[248:251], v216 offset:57344
	v_add_f32_e32 v219, v181, v219
	v_cvt_pk_bf16_f32 v173, v74, v75
	v_add_f32_e32 v219, v222, v219
	s_waitcnt lgkmcnt(3)
	v_mfma_f32_32x32x16_bf16 v[96:111], v[236:239], v[132:135], v[96:111]
	v_cvt_pk_bf16_f32 v174, v76, v77
	v_add_f32_e32 v219, v64, v219
	v_cvt_pk_bf16_f32 v175, v78, v79
	s_waitcnt lgkmcnt(2)
	v_mfma_f32_32x32x16_bf16 v[80:95], v[240:243], v[132:135], v[80:95]
	ds_read_b128 v[236:239], v217 offset:49152
	ds_read_b128 v[240:243], v217 offset:57344
	v_add_f32_e32 v219, v65, v219
	v_add_f32_e32 v219, v66, v219
	v_add_f32_e32 v219, v67, v219
	s_waitcnt lgkmcnt(3)
	v_mfma_f32_32x32x16_bf16 v[96:111], v[244:247], v[140:143], v[96:111]
	v_add_f32_e32 v219, v68, v219
	v_add_f32_e32 v219, v69, v219
	v_add_f32_e32 v219, v70, v219
	s_waitcnt lgkmcnt(2)
	v_mfma_f32_32x32x16_bf16 v[80:95], v[248:251], v[140:143], v[80:95]
	ds_read_b128 v[244:247], v218 offset:49152
	ds_read_b128 v[248:251], v218 offset:57344
	v_add_f32_e32 v219, v71, v219
	v_add_f32_e32 v219, v72, v219
	v_add_f32_e32 v219, v73, v219
	s_waitcnt lgkmcnt(3)
	v_mfma_f32_32x32x16_bf16 v[96:111], v[236:239], v[128:131], v[96:111]
	v_add_f32_e32 v219, v74, v219
	v_add_f32_e32 v219, v75, v219
	v_add_f32_e32 v219, v76, v219
	s_waitcnt lgkmcnt(2)
	v_mfma_f32_32x32x16_bf16 v[80:95], v[240:243], v[128:131], v[80:95]
	ds_read_b64_tr_b16 v[236:237], v206 offset:0
	ds_read_b64_tr_b16 v[238:239], v206 offset:2048
	ds_read_b64_tr_b16 v[240:241], v206 offset:4096
	ds_read_b64_tr_b16 v[242:243], v206 offset:6144
	v_add_f32_e32 v219, v77, v219
	v_add_f32_e32 v219, v78, v219
	v_add_f32_e32 v219, v79, v219
	s_waitcnt lgkmcnt(5)
	v_mfma_f32_32x32x16_bf16 v[96:111], v[244:247], v[136:139], v[96:111]
	v_mov_b32_e32 v220, v219
	s_nop 1
	s_waitcnt lgkmcnt(4)
	v_mfma_f32_32x32x16_bf16 v[80:95], v[248:251], v[136:139], v[80:95]
	v_permlane32_swap_b32_e32 v219, v220
	v_add_f32_e32 v219, v219, v220
	v_add_f32_e32 v204, v204, v219
	ds_read_b64_tr_b16 v[244:245], v206 offset:8192
	ds_read_b64_tr_b16 v[246:247], v206 offset:10240
	ds_read_b64_tr_b16 v[248:249], v206 offset:12288
	ds_read_b64_tr_b16 v[250:251], v206 offset:14336
	s_and_b64 vcc, exec, s[6:7]
	s_cbranch_vccnz .Lat2_noshift_A
	s_nop 15
	v_pk_add_f32 v[110:111], v[182:183], v[110:111]
	v_pk_add_f32 v[108:109], v[182:183], v[108:109]
	v_pk_add_f32 v[106:107], v[182:183], v[106:107]
	v_pk_add_f32 v[104:105], v[182:183], v[104:105]
	v_pk_add_f32 v[102:103], v[182:183], v[102:103]
	v_pk_add_f32 v[100:101], v[182:183], v[100:101]
	v_pk_add_f32 v[98:99], v[182:183], v[98:99]
	v_pk_add_f32 v[96:97], v[182:183], v[96:97]
	v_pk_add_f32 v[94:95], v[182:183], v[94:95]
	v_pk_add_f32 v[92:93], v[182:183], v[92:93]
	v_pk_add_f32 v[90:91], v[182:183], v[90:91]
	v_pk_add_f32 v[88:89], v[182:183], v[88:89]
	v_pk_add_f32 v[86:87], v[182:183], v[86:87]
	v_pk_add_f32 v[84:85], v[182:183], v[84:85]
	v_pk_add_f32 v[82:83], v[182:183], v[82:83]
	v_pk_add_f32 v[80:81], v[182:183], v[80:81]
; #define SBAR() __builtin_amdgcn_sched_barrier(0)
; #define SLOAD(i, k0) do { sr_[i].vs0 = LD8(&Vh[(long)((k0) + sr) * LDK + sc]); sr_[i].vs1 = LD8(&Vh[(long)((k0) + 32 + sr) * LDK + sc]); \
;     sr_[i].ks0 = LD8(&Kh[(long)((k0) + sr) * LDK + sc]); sr_[i].ks1 = LD8(&Kh[(long)((k0) + 32 + sr) * LDK + sc]); } while (0)
; #define SWRITE(b, i) do { *(bf16x8*)((char*)V_lds + (b) * SHM_V + vst0) = sr_[i].vs0;          \
;     *(bf16x8*)((char*)V_lds + (b) * SHM_V + vst1) = sr_[i].vs1; int kc = sc * 2;               \
;     *(bf16x8*)((char*)K_lds + (b) * SHM_K + KSWZ(sr, kc)) = sr_[i].ks0;                       \
;     *(bf16x8*)((char*)K_lds + (b) * SHM_K + KSWZ(32 + sr, kc)) = sr_[i].ks1; } while (0)
; #define SWAIT() asm volatile("s_waitcnt vmcnt(4)" ::: "memory")
; template <int D0> __device__ __forceinline__ void pv_one(f32x16& od, int vb, bf16x8 pa0, bf16x8 pa1, bf16x8 pa2, bf16x8 pa3) {
;     const s16x4 l0 = tr_read<v_rd_off(D0, 0, 0)>(vb), h0 = tr_read<v_rd_off(D0, 0, 1)>(vb), l1 = tr_read<v_rd_off(D0, 1, 0)>(vb), h1 = tr_read<v_rd_off(D0, 1, 1)>(vb);
;     const s16x4 l2 = tr_read<v_rd_off(D0, 2, 0)>(vb), h2 = tr_read<v_rd_off(D0, 2, 1)>(vb), l3 = tr_read<v_rd_off(D0, 3, 0)>(vb), h3 = tr_read<v_rd_off(D0, 3, 1)>(vb);
;     asm volatile("s_waitcnt lgkmcnt(0)" ::: "memory"); SBAR();
;     ...
;     od = __builtin_amdgcn_mfma_f32_32x32x16_bf16(pa0, PK(l0, h0), od, 0, 0, 0);
;     od = __builtin_amdgcn_mfma_f32_32x32x16_bf16(pa1, PK(l1, h1), od, 0, 0, 0);
;     od = __builtin_amdgcn_mfma_f32_32x32x16_bf16(pa2, PK(l2, h2), od, 0, 0, 0);
;     od = __builtin_amdgcn_mfma_f32_32x32x16_bf16(pa3, PK(l3, h3), od, 0, 0, 0);
;     ...
; }
; __device__ __forceinline__ void pv_d0(f32x16* o, int vb, bf16x8 pa0, bf16x8 pa1, bf16x8 pa2, bf16x8 pa3) {
;     pv_one<0>(o[0], vb, pa0, pa1, pa2, pa3); pv_one<1>(o[1], vb, pa0, pa1, pa2, pa3); pv_one<2>(o[2], vb, pa0, pa1, pa2, pa3); pv_one<3>(o[3], vb, pa0, pa1, pa2, pa3);
; __device__ __forceinline__ void attn_body(const bf16_t* __restrict__ Qb, const bf16_t* __restrict__ Kh, const bf16_t* __restrict__ Vh, const bf16_t* __restrict__ Zb, ...
;     ...
;         SLOAD(SO, (j + 2) * KVBLK); SBAR();
;         pv_d0(o, vb0, pa0, pa1, pa2, pa3); partialSM(pB0, pB1, negBC);
;         __syncthreads(); SWAIT(); SWRITE(0, SE);
.Lat2_noshift_A:
	s_waitcnt lgkmcnt(6)
	v_mfma_f32_32x32x16_bf16 v[0:15], v[160:163], v[236:239], v[0:15]
	ds_read_b64_tr_b16 v[236:237], v206 offset:512
	ds_read_b64_tr_b16 v[238:239], v206 offset:2560
	s_waitcnt lgkmcnt(6)
	v_mfma_f32_32x32x16_bf16 v[0:15], v[164:167], v[240:243], v[0:15]
	ds_read_b64_tr_b16 v[240:241], v206 offset:4608
	ds_read_b64_tr_b16 v[242:243], v206 offset:6656
	s_waitcnt vmcnt(0)
	ds_write_b128 v209, v[148:151] offset:32768
	v_exp_f32_e32 v181, v96
	v_exp_f32_e32 v221, v97
	s_waitcnt lgkmcnt(7)
	v_mfma_f32_32x32x16_bf16 v[0:15], v[168:171], v[244:247], v[0:15]
	ds_read_b64_tr_b16 v[244:245], v206 offset:8704
	ds_read_b64_tr_b16 v[246:247], v206 offset:10752
	ds_write_b128 v210, v[152:155] offset:32768
	v_exp_f32_e32 v222, v98
	v_exp_f32_e32 v223, v99
	s_waitcnt lgkmcnt(8)
	v_mfma_f32_32x32x16_bf16 v[0:15], v[172:175], v[248:251], v[0:15]
	ds_read_b64_tr_b16 v[248:249], v206 offset:12800
	ds_read_b64_tr_b16 v[250:251], v206 offset:14848
	ds_write_b128 v252, v[144:147] offset:16384
	v_exp_f32_e32 v224, v100
	v_exp_f32_e32 v225, v101
	s_waitcnt lgkmcnt(9)
	v_mfma_f32_32x32x16_bf16 v[16:31], v[160:163], v[236:239], v[16:31]
	ds_read_b64_tr_b16 v[236:237], v206 offset:1024
	ds_read_b64_tr_b16 v[238:239], v206 offset:3072
	ds_write_b128 v253, v[156:159] offset:16384
	v_exp_f32_e32 v226, v102
	v_exp_f32_e32 v227, v103
	s_waitcnt lgkmcnt(10)
	v_mfma_f32_32x32x16_bf16 v[16:31], v[164:167], v[240:243], v[16:31]
	ds_read_b64_tr_b16 v[240:241], v206 offset:5120
	ds_read_b64_tr_b16 v[242:243], v206 offset:7168
	v_exp_f32_e32 v228, v104
	v_exp_f32_e32 v229, v105
	s_waitcnt lgkmcnt(9)
	v_mfma_f32_32x32x16_bf16 v[16:31], v[168:171], v[244:247], v[16:31]
	ds_read_b64_tr_b16 v[244:245], v206 offset:9216
	ds_read_b64_tr_b16 v[246:247], v206 offset:11264
	v_lshl_add_u64 v[144:145], v[190:191], 0, s[98:99]
	global_load_dwordx4 v[156:159], v[190:191], off
	global_load_dwordx4 v[144:147], v[144:145], off
	v_exp_f32_e32 v230, v106
	v_exp_f32_e32 v231, v107
	s_waitcnt lgkmcnt(8)
	v_mfma_f32_32x32x16_bf16 v[16:31], v[172:175], v[248:251], v[16:31]
	ds_read_b64_tr_b16 v[248:249], v206 offset:13312
	ds_read_b64_tr_b16 v[250:251], v206 offset:15360
	v_exp_f32_e32 v232, v108
	v_exp_f32_e32 v233, v109
	s_waitcnt lgkmcnt(7)
	v_mfma_f32_32x32x16_bf16 v[32:47], v[160:163], v[236:239], v[32:47]
	ds_read_b64_tr_b16 v[236:237], v206 offset:1536
	ds_read_b64_tr_b16 v[238:239], v206 offset:3584
	v_lshl_add_u64 v[190:191], v[190:191], 0, s[100:101]
	v_lshl_add_u64 v[148:149], v[190:191], 0, s[98:99]
	global_load_dwordx4 v[152:155], v[190:191], off offset:-512
	global_load_dwordx4 v[148:151], v[148:149], off offset:-512
	v_exp_f32_e32 v234, v110
	v_exp_f32_e32 v235, v111
	s_waitcnt lgkmcnt(6)
	v_mfma_f32_32x32x16_bf16 v[32:47], v[164:167], v[240:243], v[32:47]
	ds_read_b64_tr_b16 v[240:241], v206 offset:5632
	ds_read_b64_tr_b16 v[242:243], v206 offset:7680
	v_exp_f32_e32 v80, v80
	v_exp_f32_e32 v81, v81
	s_waitcnt lgkmcnt(6)
	v_mfma_f32_32x32x16_bf16 v[32:47], v[168:171], v[244:247], v[32:47]
	ds_read_b64_tr_b16 v[244:245], v206 offset:9728
	ds_read_b64_tr_b16 v[246:247], v206 offset:11776
	v_exp_f32_e32 v82, v82
	v_exp_f32_e32 v83, v83
	s_waitcnt lgkmcnt(6)
	v_mfma_f32_32x32x16_bf16 v[32:47], v[172:175], v[248:251], v[32:47]
	ds_read_b64_tr_b16 v[248:249], v206 offset:13824
	ds_read_b64_tr_b16 v[250:251], v206 offset:15872
	v_exp_f32_e32 v84, v84
	v_exp_f32_e32 v85, v85
	s_waitcnt lgkmcnt(6)
	v_mfma_f32_32x32x16_bf16 v[48:63], v[160:163], v[236:239], v[48:63]
	v_exp_f32_e32 v86, v86
	v_exp_f32_e32 v87, v87
	s_waitcnt lgkmcnt(4)
	v_mfma_f32_32x32x16_bf16 v[48:63], v[164:167], v[240:243], v[48:63]
	v_exp_f32_e32 v88, v88
	v_exp_f32_e32 v89, v89
	v_exp_f32_e32 v90, v90
	s_waitcnt lgkmcnt(2)
	v_mfma_f32_32x32x16_bf16 v[48:63], v[168:171], v[244:247], v[48:63]
	v_exp_f32_e32 v91, v91
	v_exp_f32_e32 v92, v92
	v_exp_f32_e32 v93, v93
	s_waitcnt lgkmcnt(0)
	v_mfma_f32_32x32x16_bf16 v[48:63], v[172:175], v[248:251], v[48:63]
	v_exp_f32_e32 v94, v94
	v_exp_f32_e32 v95, v95
	v_mov_b32_e32 v252, v207
	v_mov_b32_e32 v253, v208
	s_waitcnt lgkmcnt(0)
	s_barrier
; __device__ __forceinline__ void finishSM(f32x16& p0, f32x16& p1, float alpha, float& l_reg, bf16x8& pa0, bf16x8& pa1, bf16x8& pa2, bf16x8& pa3) {
;     for (int r = 0; r < 16; ++r) p1[r] = __builtin_amdgcn_exp2f(p1[r]);
;     float ps = 0; for (int r = 0; r < 16; ++r) ps += p0[r]; for (int r = 0; r < 16; ++r) ps += p1[r];
;     { auto rr = __builtin_amdgcn_permlane32_swap(__float_as_uint(ps), __float_as_uint(ps), false, false);
;       ps = __uint_as_float(rr[0]) + __uint_as_float(rr[1]); }
;     l_reg = l_reg * alpha + ps;
;     ...
;     PK4(p0, 0, pa0); PK4(p0, 8, pa1); PK4(p1, 0, pa2); PK4(p1, 8, pa3);
;     ...
; }
; __device__ __forceinline__ void qkt(f32x16& p0, f32x16& p1, const bf16_t* Ks, const bf16x8* qr, int r32, int hi) {
;     p0 = f32x16{}; p1 = f32x16{};
;     for (int d0 = 0; d0 < 8; ++d0) { int cb = (d0 * 16 + hi * 8) * 2;
;         bf16x8 b0 = *reinterpret_cast<const bf16x8*>((const char*)Ks + KSWZ(r32, cb));
;         bf16x8 b1 = *reinterpret_cast<const bf16x8*>((const char*)Ks + KSWZ(32 + r32, cb));
;         p0 = __builtin_amdgcn_mfma_f32_32x32x16_bf16(b0, qr[d0], p0, 0, 0, 0);
;         p1 = __builtin_amdgcn_mfma_f32_32x32x16_bf16(b1, qr[d0], p1, 0, 0, 0); }
; }
	ds_read_b128 v[236:239], v211 offset:32768
	ds_read_b128 v[240:243], v211 offset:40960
	ds_read_b128 v[244:247], v212 offset:32768
	ds_read_b128 v[248:251], v212 offset:40960
	v_add_f32_e32 v219, v181, v221
	v_cvt_pk_bf16_f32 v160, v181, v221
	v_add_f32_e32 v219, v222, v219
	s_waitcnt lgkmcnt(3)
	v_mfma_f32_32x32x16_bf16 v[96:111], v[236:239], v[116:119], 0
	v_cvt_pk_bf16_f32 v161, v222, v223
	v_add_f32_e32 v219, v223, v219
	v_cvt_pk_bf16_f32 v162, v224, v225
	v_add_f32_e32 v219, v224, v219
	s_waitcnt lgkmcnt(2)
	v_mfma_f32_32x32x16_bf16 v[64:79], v[240:243], v[116:119], 0
	ds_read_b128 v[236:239], v213 offset:32768
	ds_read_b128 v[240:243], v213 offset:40960
	v_cvt_pk_bf16_f32 v163, v226, v227
	v_add_f32_e32 v219, v225, v219
	v_cvt_pk_bf16_f32 v164, v228, v229
	v_add_f32_e32 v219, v226, v219
	s_waitcnt lgkmcnt(3)
	v_mfma_f32_32x32x16_bf16 v[96:111], v[244:247], v[124:127], v[96:111]
	v_cvt_pk_bf16_f32 v165, v230, v231
	v_add_f32_e32 v219, v227, v219
	v_cvt_pk_bf16_f32 v166, v232, v233
	s_waitcnt lgkmcnt(2)
	v_mfma_f32_32x32x16_bf16 v[64:79], v[248:251], v[124:127], v[64:79]
	ds_read_b128 v[244:247], v214 offset:32768
	ds_read_b128 v[248:251], v214 offset:40960
	v_add_f32_e32 v219, v228, v219
	v_cvt_pk_bf16_f32 v167, v234, v235
	v_add_f32_e32 v219, v229, v219
	s_waitcnt lgkmcnt(3)
	v_mfma_f32_32x32x16_bf16 v[96:111], v[236:239], v[112:115], v[96:111]
	v_cvt_pk_bf16_f32 v168, v80, v81
	v_add_f32_e32 v219, v230, v219
	v_cvt_pk_bf16_f32 v169, v82, v83
	s_waitcnt lgkmcnt(2)
	v_mfma_f32_32x32x16_bf16 v[64:79], v[240:243], v[112:115], v[64:79]
	ds_read_b128 v[236:239], v215 offset:32768
	ds_read_b128 v[240:243], v215 offset:40960
	v_add_f32_e32 v219, v231, v219
	v_cvt_pk_bf16_f32 v170, v84, v85
	v_add_f32_e32 v219, v232, v219
	s_waitcnt lgkmcnt(3)
	v_mfma_f32_32x32x16_bf16 v[96:111], v[244:247], v[120:123], v[96:111]
	v_cvt_pk_bf16_f32 v171, v86, v87
	v_add_f32_e32 v219, v233, v219
	v_cvt_pk_bf16_f32 v172, v88, v89
	s_waitcnt lgkmcnt(2)
	v_mfma_f32_32x32x16_bf16 v[64:79], v[248:251], v[120:123], v[64:79]
	ds_read_b128 v[244:247], v216 offset:32768
	ds_read_b128 v[248:251], v216 offset:40960
	v_add_f32_e32 v219, v234, v219
	v_cvt_pk_bf16_f32 v173, v90, v91
	v_add_f32_e32 v219, v235, v219
	s_waitcnt lgkmcnt(3)
	v_mfma_f32_32x32x16_bf16 v[96:111], v[236:239], v[132:135], v[96:111]
	v_cvt_pk_bf16_f32 v174, v92, v93
	v_add_f32_e32 v219, v80, v219
	v_cvt_pk_bf16_f32 v175, v94, v95
	s_waitcnt lgkmcnt(2)
	v_mfma_f32_32x32x16_bf16 v[64:79], v[240:243], v[132:135], v[64:79]
	ds_read_b128 v[236:239], v217 offset:32768
	ds_read_b128 v[240:243], v217 offset:40960
	v_add_f32_e32 v219, v81, v219
	v_add_f32_e32 v219, v82, v219
	v_add_f32_e32 v219, v83, v219
	s_waitcnt lgkmcnt(3)
	v_mfma_f32_32x32x16_bf16 v[96:111], v[244:247], v[140:143], v[96:111]
	v_add_f32_e32 v219, v84, v219
	v_add_f32_e32 v219, v85, v219
	v_add_f32_e32 v219, v86, v219
	s_waitcnt lgkmcnt(2)
	v_mfma_f32_32x32x16_bf16 v[64:79], v[248:251], v[140:143], v[64:79]
	ds_read_b128 v[244:247], v218 offset:32768
	ds_read_b128 v[248:251], v218 offset:40960
	v_add_f32_e32 v219, v87, v219
	v_add_f32_e32 v219, v88, v219
	v_add_f32_e32 v219, v89, v219
	s_waitcnt lgkmcnt(3)
	v_mfma_f32_32x32x16_bf16 v[96:111], v[236:239], v[128:131], v[96:111]
	v_add_f32_e32 v219, v90, v219
	v_add_f32_e32 v219, v91, v219
	v_add_f32_e32 v219, v92, v219
	s_waitcnt lgkmcnt(2)
	v_mfma_f32_32x32x16_bf16 v[64:79], v[240:243], v[128:131], v[64:79]
	ds_read_b64_tr_b16 v[236:237], v205 offset:0
	ds_read_b64_tr_b16 v[238:239], v205 offset:2048
	ds_read_b64_tr_b16 v[240:241], v205 offset:4096
	ds_read_b64_tr_b16 v[242:243], v205 offset:6144
	v_add_f32_e32 v219, v93, v219
	v_add_f32_e32 v219, v94, v219
	v_add_f32_e32 v219, v95, v219
	s_waitcnt lgkmcnt(5)
	v_mfma_f32_32x32x16_bf16 v[96:111], v[244:247], v[136:139], v[96:111]
	v_mov_b32_e32 v220, v219
	s_nop 1
	s_waitcnt lgkmcnt(4)
	v_mfma_f32_32x32x16_bf16 v[64:79], v[248:251], v[136:139], v[64:79]
	v_permlane32_swap_b32_e32 v219, v220
	v_add_f32_e32 v219, v219, v220
	v_add_f32_e32 v204, v204, v219
	ds_read_b64_tr_b16 v[244:245], v205 offset:8192
	ds_read_b64_tr_b16 v[246:247], v205 offset:10240
	ds_read_b64_tr_b16 v[248:249], v205 offset:12288
	ds_read_b64_tr_b16 v[250:251], v205 offset:14336
	s_and_b64 vcc, exec, s[6:7]
	s_cbranch_vccnz .Lat2_noshift_B
	s_nop 15
	v_pk_add_f32 v[110:111], v[182:183], v[110:111]
	v_pk_add_f32 v[108:109], v[182:183], v[108:109]
	v_pk_add_f32 v[106:107], v[182:183], v[106:107]
	v_pk_add_f32 v[104:105], v[182:183], v[104:105]
	v_pk_add_f32 v[102:103], v[182:183], v[102:103]
	v_pk_add_f32 v[100:101], v[182:183], v[100:101]
	v_pk_add_f32 v[98:99], v[182:183], v[98:99]
	v_pk_add_f32 v[96:97], v[182:183], v[96:97]
	v_pk_add_f32 v[78:79], v[182:183], v[78:79]
	v_pk_add_f32 v[76:77], v[182:183], v[76:77]
	v_pk_add_f32 v[74:75], v[182:183], v[74:75]
	v_pk_add_f32 v[72:73], v[182:183], v[72:73]
	v_pk_add_f32 v[70:71], v[182:183], v[70:71]
	v_pk_add_f32 v[68:69], v[182:183], v[68:69]
	v_pk_add_f32 v[66:67], v[182:183], v[66:67]
	v_pk_add_f32 v[64:65], v[182:183], v[64:65]

; #define SBAR() __builtin_amdgcn_sched_barrier(0)
; template <int D0> __device__ __forceinline__ void pv_one(f32x16& od, int vb, bf16x8 pa0, bf16x8 pa1, bf16x8 pa2, bf16x8 pa3) {
;     const s16x4 l0 = tr_read<v_rd_off(D0, 0, 0)>(vb), h0 = tr_read<v_rd_off(D0, 0, 1)>(vb), l1 = tr_read<v_rd_off(D0, 1, 0)>(vb), h1 = tr_read<v_rd_off(D0, 1, 1)>(vb);
;     const s16x4 l2 = tr_read<v_rd_off(D0, 2, 0)>(vb), h2 = tr_read<v_rd_off(D0, 2, 1)>(vb), l3 = tr_read<v_rd_off(D0, 3, 0)>(vb), h3 = tr_read<v_rd_off(D0, 3, 1)>(vb);
;     asm volatile("s_waitcnt lgkmcnt(0)" ::: "memory"); SBAR();
;     ...
;     od = __builtin_amdgcn_mfma_f32_32x32x16_bf16(pa0, PK(l0, h0), od, 0, 0, 0);
;     od = __builtin_amdgcn_mfma_f32_32x32x16_bf16(pa1, PK(l1, h1), od, 0, 0, 0);
;     od = __builtin_amdgcn_mfma_f32_32x32x16_bf16(pa2, PK(l2, h2), od, 0, 0, 0);
;     od = __builtin_amdgcn_mfma_f32_32x32x16_bf16(pa3, PK(l3, h3), od, 0, 0, 0);
;     ...
; }
; __device__ __forceinline__ void pv_d0(f32x16* o, int vb, bf16x8 pa0, bf16x8 pa1, bf16x8 pa2, bf16x8 pa3) {
;     pv_one<0>(o[0], vb, pa0, pa1, pa2, pa3); pv_one<1>(o[1], vb, pa0, pa1, pa2, pa3); pv_one<2>(o[2], vb, pa0, pa1, pa2, pa3); pv_one<3>(o[3], vb, pa0, pa1, pa2, pa3);
; __device__ __forceinline__ void attn_body(const bf16_t* __restrict__ Qb, const bf16_t* __restrict__ Kh, const bf16_t* __restrict__ Vh, const bf16_t* __restrict__ Zb, ...
;     ...
;     SBAR(); qkt(pB0, pB1, (bf16_t*)((char*)K_lds + SHM_K), qr, r32, hi);
;     finishSM(pA0, pA1, 1.f, l_reg, pa0, pa1, pa2, pa3); SBAR();
;     pv_d0(o, vb0, pa0, pa1, pa2, pa3); partialSM(pB0, pB1, negBC);
;     __syncthreads();
.Lat2_noshift_TA:
	s_waitcnt lgkmcnt(6)
	v_mfma_f32_32x32x16_bf16 v[0:15], v[160:163], v[236:239], v[0:15]
	ds_read_b64_tr_b16 v[236:237], v206 offset:512
	ds_read_b64_tr_b16 v[238:239], v206 offset:2560
	s_waitcnt lgkmcnt(6)
	v_mfma_f32_32x32x16_bf16 v[0:15], v[164:167], v[240:243], v[0:15]
	ds_read_b64_tr_b16 v[240:241], v206 offset:4608
	ds_read_b64_tr_b16 v[242:243], v206 offset:6656
	s_waitcnt vmcnt(0)
	ds_write_b128 v207, v[144:147] offset:16384
	v_exp_f32_e32 v181, v96
	v_exp_f32_e32 v221, v97
	s_waitcnt lgkmcnt(7)
	v_mfma_f32_32x32x16_bf16 v[0:15], v[168:171], v[244:247], v[0:15]
	ds_read_b64_tr_b16 v[244:245], v206 offset:8704
	ds_read_b64_tr_b16 v[246:247], v206 offset:10752
	ds_write_b128 v208, v[156:159] offset:16384
	v_exp_f32_e32 v222, v98
	v_exp_f32_e32 v223, v99
	s_waitcnt lgkmcnt(8)
	v_mfma_f32_32x32x16_bf16 v[0:15], v[172:175], v[248:251], v[0:15]
	ds_read_b64_tr_b16 v[248:249], v206 offset:12800
	ds_read_b64_tr_b16 v[250:251], v206 offset:14848
	v_exp_f32_e32 v224, v100
	v_exp_f32_e32 v225, v101
	s_waitcnt lgkmcnt(8)
	v_mfma_f32_32x32x16_bf16 v[16:31], v[160:163], v[236:239], v[16:31]
	ds_read_b64_tr_b16 v[236:237], v206 offset:1024
	ds_read_b64_tr_b16 v[238:239], v206 offset:3072
	v_exp_f32_e32 v226, v102
	v_exp_f32_e32 v227, v103
	s_waitcnt lgkmcnt(8)
	v_mfma_f32_32x32x16_bf16 v[16:31], v[164:167], v[240:243], v[16:31]
	ds_read_b64_tr_b16 v[240:241], v206 offset:5120
	ds_read_b64_tr_b16 v[242:243], v206 offset:7168
	v_exp_f32_e32 v228, v104
	v_exp_f32_e32 v229, v105
	s_waitcnt lgkmcnt(7)
	v_mfma_f32_32x32x16_bf16 v[16:31], v[168:171], v[244:247], v[16:31]
	ds_read_b64_tr_b16 v[244:245], v206 offset:9216
	ds_read_b64_tr_b16 v[246:247], v206 offset:11264
	v_exp_f32_e32 v230, v106
	v_exp_f32_e32 v231, v107
	s_waitcnt lgkmcnt(6)
	v_mfma_f32_32x32x16_bf16 v[16:31], v[172:175], v[248:251], v[16:31]
	ds_read_b64_tr_b16 v[248:249], v206 offset:13312
	ds_read_b64_tr_b16 v[250:251], v206 offset:15360
	v_exp_f32_e32 v232, v108
	v_exp_f32_e32 v233, v109
	s_waitcnt lgkmcnt(6)
	v_mfma_f32_32x32x16_bf16 v[32:47], v[160:163], v[236:239], v[32:47]
	ds_read_b64_tr_b16 v[236:237], v206 offset:1536
	ds_read_b64_tr_b16 v[238:239], v206 offset:3584
	v_exp_f32_e32 v234, v110
	v_exp_f32_e32 v235, v111
	s_waitcnt lgkmcnt(6)
	v_mfma_f32_32x32x16_bf16 v[32:47], v[164:167], v[240:243], v[32:47]
	ds_read_b64_tr_b16 v[240:241], v206 offset:5632
	ds_read_b64_tr_b16 v[242:243], v206 offset:7680
	v_exp_f32_e32 v80, v80
	v_exp_f32_e32 v81, v81
	s_waitcnt lgkmcnt(6)
	v_mfma_f32_32x32x16_bf16 v[32:47], v[168:171], v[244:247], v[32:47]
	ds_read_b64_tr_b16 v[244:245], v206 offset:9728
	ds_read_b64_tr_b16 v[246:247], v206 offset:11776
	v_exp_f32_e32 v82, v82
	v_exp_f32_e32 v83, v83
	s_waitcnt lgkmcnt(6)
	v_mfma_f32_32x32x16_bf16 v[32:47], v[172:175], v[248:251], v[32:47]
	ds_read_b64_tr_b16 v[248:249], v206 offset:13824
	ds_read_b64_tr_b16 v[250:251], v206 offset:15872
	v_exp_f32_e32 v84, v84
	v_exp_f32_e32 v85, v85
	s_waitcnt lgkmcnt(6)
	v_mfma_f32_32x32x16_bf16 v[48:63], v[160:163], v[236:239], v[48:63]
	v_exp_f32_e32 v86, v86
	v_exp_f32_e32 v87, v87
	s_waitcnt lgkmcnt(4)
	v_mfma_f32_32x32x16_bf16 v[48:63], v[164:167], v[240:243], v[48:63]
	v_exp_f32_e32 v88, v88
	v_exp_f32_e32 v89, v89
	v_exp_f32_e32 v90, v90
	s_waitcnt lgkmcnt(2)
	v_mfma_f32_32x32x16_bf16 v[48:63], v[168:171], v[244:247], v[48:63]
	v_exp_f32_e32 v91, v91
	v_exp_f32_e32 v92, v92
	v_exp_f32_e32 v93, v93
	s_waitcnt lgkmcnt(0)
	v_mfma_f32_32x32x16_bf16 v[48:63], v[172:175], v[248:251], v[48:63]
	v_exp_f32_e32 v94, v94
	v_exp_f32_e32 v95, v95
	s_waitcnt lgkmcnt(0)
	s_barrier
; #define SBAR() __builtin_amdgcn_sched_barrier(0)
; __device__ __forceinline__ void finishSM(f32x16& p0, f32x16& p1, float alpha, float& l_reg, bf16x8& pa0, bf16x8& pa1, bf16x8& pa2, bf16x8& pa3) {
;     for (int r = 0; r < 16; ++r) p1[r] = __builtin_amdgcn_exp2f(p1[r]);
;     float ps = 0; for (int r = 0; r < 16; ++r) ps += p0[r]; for (int r = 0; r < 16; ++r) ps += p1[r];
;     { auto rr = __builtin_amdgcn_permlane32_swap(__float_as_uint(ps), __float_as_uint(ps), false, false);
;       ps = __uint_as_float(rr[0]) + __uint_as_float(rr[1]); }
;     l_reg = l_reg * alpha + ps;
;     ...
;     PK4(p0, 0, pa0); PK4(p0, 8, pa1); PK4(p1, 0, pa2); PK4(p1, 8, pa3);
;     ...
; }
; __device__ __forceinline__ void attn_body(const bf16_t* __restrict__ Qb, const bf16_t* __restrict__ Kh, const bf16_t* __restrict__ Vh, const bf16_t* __restrict__ Zb, ...
;     ...
;     finishSM(pB0, pB1, 1.f, l_reg, pa0, pa1, pa2, pa3); SBAR();
;     pv_d0(o, vb0 + (int)SHM_V, pa0, pa1, pa2, pa3);
;     __builtin_amdgcn_s_setprio(0);
;     if (hi == 0) li_l[r32] = l_reg; asm volatile("s_waitcnt lgkmcnt(0)" ::: "memory");
	ds_read_b64_tr_b16 v[236:237], v205 offset:0
	ds_read_b64_tr_b16 v[238:239], v205 offset:2048
	ds_read_b64_tr_b16 v[240:241], v205 offset:4096
	ds_read_b64_tr_b16 v[242:243], v205 offset:6144
	ds_read_b64_tr_b16 v[244:245], v205 offset:8192
	ds_read_b64_tr_b16 v[246:247], v205 offset:10240
	ds_read_b64_tr_b16 v[248:249], v205 offset:12288
	ds_read_b64_tr_b16 v[250:251], v205 offset:14336
	v_add_f32_e32 v219, v181, v221
	v_cvt_pk_bf16_f32 v160, v181, v221
	v_add_f32_e32 v219, v222, v219
	v_cvt_pk_bf16_f32 v161, v222, v223
	v_add_f32_e32 v219, v223, v219
	v_cvt_pk_bf16_f32 v162, v224, v225
	v_add_f32_e32 v219, v224, v219
	v_cvt_pk_bf16_f32 v163, v226, v227
	v_add_f32_e32 v219, v225, v219
	v_cvt_pk_bf16_f32 v164, v228, v229
	v_add_f32_e32 v219, v226, v219
	v_cvt_pk_bf16_f32 v165, v230, v231
	v_add_f32_e32 v219, v227, v219
	v_cvt_pk_bf16_f32 v166, v232, v233
	v_add_f32_e32 v219, v228, v219
	v_cvt_pk_bf16_f32 v167, v234, v235
	v_add_f32_e32 v219, v229, v219
	v_cvt_pk_bf16_f32 v168, v80, v81
	v_add_f32_e32 v219, v230, v219
	v_cvt_pk_bf16_f32 v169, v82, v83
	v_add_f32_e32 v219, v231, v219
	v_cvt_pk_bf16_f32 v170, v84, v85
	v_add_f32_e32 v219, v232, v219
	v_cvt_pk_bf16_f32 v171, v86, v87
	v_add_f32_e32 v219, v233, v219
	v_cvt_pk_bf16_f32 v172, v88, v89
	v_add_f32_e32 v219, v234, v219
	v_cvt_pk_bf16_f32 v173, v90, v91
	v_add_f32_e32 v219, v235, v219
	v_cvt_pk_bf16_f32 v174, v92, v93
	v_add_f32_e32 v219, v80, v219
	v_cvt_pk_bf16_f32 v175, v94, v95
	v_add_f32_e32 v219, v81, v219
	v_add_f32_e32 v219, v82, v219
	v_add_f32_e32 v219, v83, v219
	v_add_f32_e32 v219, v84, v219
	v_add_f32_e32 v219, v85, v219
	v_add_f32_e32 v219, v86, v219
	v_add_f32_e32 v219, v87, v219
	v_add_f32_e32 v219, v88, v219
	v_add_f32_e32 v219, v89, v219
	v_add_f32_e32 v219, v90, v219
	v_add_f32_e32 v219, v91, v219
	v_add_f32_e32 v219, v92, v219
	v_add_f32_e32 v219, v93, v219
	v_add_f32_e32 v219, v94, v219
	v_add_f32_e32 v219, v95, v219
	v_mov_b32_e32 v220, v219
	s_nop 1
	v_permlane32_swap_b32_e32 v219, v220
	v_add_f32_e32 v219, v219, v220
	v_add_f32_e32 v204, v204, v219
	s_waitcnt lgkmcnt(6)
	v_mfma_f32_32x32x16_bf16 v[0:15], v[160:163], v[236:239], v[0:15]
	ds_read_b64_tr_b16 v[236:237], v205 offset:512
	ds_read_b64_tr_b16 v[238:239], v205 offset:2560
	s_waitcnt lgkmcnt(6)
	v_mfma_f32_32x32x16_bf16 v[0:15], v[164:167], v[240:243], v[0:15]
	ds_read_b64_tr_b16 v[240:241], v205 offset:4608
	ds_read_b64_tr_b16 v[242:243], v205 offset:6656
	s_waitcnt lgkmcnt(6)
	v_mfma_f32_32x32x16_bf16 v[0:15], v[168:171], v[244:247], v[0:15]
	ds_read_b64_tr_b16 v[244:245], v205 offset:8704
	ds_read_b64_tr_b16 v[246:247], v205 offset:10752
	s_waitcnt lgkmcnt(6)
	v_mfma_f32_32x32x16_bf16 v[0:15], v[172:175], v[248:251], v[0:15]
	ds_read_b64_tr_b16 v[248:249], v205 offset:12800
	ds_read_b64_tr_b16 v[250:251], v205 offset:14848
	s_waitcnt lgkmcnt(6)
	v_mfma_f32_32x32x16_bf16 v[16:31], v[160:163], v[236:239], v[16:31]
	ds_read_b64_tr_b16 v[236:237], v205 offset:1024
	ds_read_b64_tr_b16 v[238:239], v205 offset:3072
	s_waitcnt lgkmcnt(6)
	v_mfma_f32_32x32x16_bf16 v[16:31], v[164:167], v[240:243], v[16:31]
	ds_read_b64_tr_b16 v[240:241], v205 offset:5120
	ds_read_b64_tr_b16 v[242:243], v205 offset:7168
	s_waitcnt lgkmcnt(6)
	v_mfma_f32_32x32x16_bf16 v[16:31], v[168:171], v[244:247], v[16:31]
	ds_read_b64_tr_b16 v[244:245], v205 offset:9216
	ds_read_b64_tr_b16 v[246:247], v205 offset:11264
	s_waitcnt lgkmcnt(6)
	v_mfma_f32_32x32x16_bf16 v[16:31], v[172:175], v[248:251], v[16:31]
	ds_read_b64_tr_b16 v[248:249], v205 offset:13312
	ds_read_b64_tr_b16 v[250:251], v205 offset:15360
	s_waitcnt lgkmcnt(6)
	v_mfma_f32_32x32x16_bf16 v[32:47], v[160:163], v[236:239], v[32:47]
	ds_read_b64_tr_b16 v[236:237], v205 offset:1536
	ds_read_b64_tr_b16 v[238:239], v205 offset:3584
	s_waitcnt lgkmcnt(6)
	v_mfma_f32_32x32x16_bf16 v[32:47], v[164:167], v[240:243], v[32:47]
	ds_read_b64_tr_b16 v[240:241], v205 offset:5632
	ds_read_b64_tr_b16 v[242:243], v205 offset:7680
	s_waitcnt lgkmcnt(6)
	v_mfma_f32_32x32x16_bf16 v[32:47], v[168:171], v[244:247], v[32:47]
	ds_read_b64_tr_b16 v[244:245], v205 offset:9728
	ds_read_b64_tr_b16 v[246:247], v205 offset:11776
	s_waitcnt lgkmcnt(6)
	v_mfma_f32_32x32x16_bf16 v[32:47], v[172:175], v[248:251], v[32:47]
	ds_read_b64_tr_b16 v[248:249], v205 offset:13824
	ds_read_b64_tr_b16 v[250:251], v205 offset:15872
	s_waitcnt lgkmcnt(6)
	v_mfma_f32_32x32x16_bf16 v[48:63], v[160:163], v[236:239], v[48:63]
	s_waitcnt lgkmcnt(4)
	v_mfma_f32_32x32x16_bf16 v[48:63], v[164:167], v[240:243], v[48:63]
	s_waitcnt lgkmcnt(2)
	v_mfma_f32_32x32x16_bf16 v[48:63], v[168:171], v[244:247], v[48:63]
	s_waitcnt lgkmcnt(0)
	v_mfma_f32_32x32x16_bf16 v[48:63], v[172:175], v[248:251], v[48:63]
	v_mov_b32_e32 v64, 0
	v_mov_b32_e32 v65, 0
	v_mov_b32_e32 v67, 0
	v_mov_b32_e32 v68, 0
	v_and_b32_e32 v66, 0x3fffffc0, v200
	v_lshl_add_u32 v66, v66, 2, s36
	s_setprio 0
	v_cmp_gt_u32_e32 vcc, 32, v203
	s_and_saveexec_b64 s[6:7], vcc
	s_cbranch_execz .LBB0_480
	v_add_f32_e32 v64, v64, v65
	v_add_f32_e32 v64, v204, v64
	v_add_f32_e32 v67, v67, v68
	v_lshl_add_u32 v65, v201, 2, v66
	v_add_f32_e32 v64, v64, v67
	ds_write_b32 v65, v64
	s_branch .LBB0_480
